# scan phase: per-chunk s_barrier replaced by LDS progress words between staging and scan waves, scan pipeline runs continuously across chunks
# baseline (speedup 1.0000x reference)
.LBB0_41:
	s_andn2_b64 vcc, exec, s[6:7]
	s_cbranch_vccnz .LBB0_61
	v_readlane_b32 s4, v242, 4
	v_readlane_b32 s5, v242, 5
	v_mov_b32_e32 v8, v173
	s_andn2_b64 vcc, exec, s[4:5]
	s_cbranch_vccnz .LBB0_61
	v_lshrrev_b32_e32 v0, 6, v173
	s_mov_b32 s4, s2
	s_nop 3
	v_readfirstlane_b32 s7, v0
	v_readlane_b32 s15, v240, 63
.Lsc_item:
	v_lshlrev_b32_e32 v164, 2, v0
	v_add_u32_e32 v164, 121856, v164
	v_xor_b32_e32 v164, 16, v164
	ds_write_b32 v164, v169
	s_waitcnt lgkmcnt(0)
	s_barrier
	s_cmp_ge_u32 s7, 4
	s_cbranch_scc1 .Lsc_G
	v_lshlrev_b32_e32 v27, 2, v173
	v_and_b32_e32 v27, 60, v27
	v_lshlrev_b32_e32 v7, 2, v0
	v_bfe_u32 v1, v173, 4, 2
	v_or_b32_e32 v37, v7, v1
	v_lshlrev_b32_e32 v37, 5, v37
	v_and_b32_e32 v36, 7, v173
	v_lshl_add_u32 v37, v36, 2, v37
	v_add_u32_e32 v37, 89088, v37
	v_and_b32_e32 v34, 15, v173
	v_lshlrev_b32_e32 v34, 4, v34
	v_or_b32_e32 v35, v7, v1
	v_mul_u32_u24_e32 v35, 144, v35
	v_add_u32_e32 v35, 84480, v35
	v_mov_b32_e32 v8, 0
	v_mov_b32_e32 v9, 0
	v_mov_b32_e32 v10, 0
	v_mov_b32_e32 v11, 0
	v_add_u32_e32 v48, 42240, v34
	v_add_u32_e32 v49, 2304, v35
	v_add_u32_e32 v50, 0x4000, v37
	v_mov_b32_e32 v51, 0
	v_mov_b32_e32 v52, 121856
	v_mov_b32_e32 v53, v164
	s_mov_b32 s6, 0
	s_mov_b32 s55, 0x100000
.Lsc_S_w0:
	ds_read_b128 v[56:59], v52
	s_waitcnt lgkmcnt(0)
	v_min_u32_e32 v56, v56, v57
	v_min3_u32 v56, v56, v58, v59
	s_sub_u32 s55, s55, 1
	s_nop 1
	v_readfirstlane_b32 s54, v56
	s_cmp_eq_u32 s55, 0
	s_cbranch_scc1 .Lsc_S_go
	s_cmp_lt_u32 s54, 1
	s_cbranch_scc1 .Lsc_S_w0
.Lsc_S_go:
	ds_read_b128 v[40:43], v34 offset:41728
	ds_read_b128 v[44:47], v34 offset:41984
	ds_read_b128 v[156:159], v35 offset:0
	ds_read_b128 v[76:79], v34 offset:0
	ds_read_b128 v[80:83], v34 offset:256
	ds_read_b128 v[84:87], v34 offset:512
	ds_read_b128 v[88:91], v34 offset:768
	ds_read_b128 v[92:95], v34 offset:1024
	ds_read_b128 v[96:99], v34 offset:1280
	ds_read_b128 v[100:103], v34 offset:1536
	ds_read_b128 v[104:107], v34 offset:1792
	ds_read_b128 v[108:111], v34 offset:2048
	ds_read_b128 v[112:115], v34 offset:2304
	s_waitcnt lgkmcnt(12)
	v_mul_f32_e32 v24, v10, v40
	v_fmac_f32_e32 v24, v11, v42
	s_waitcnt lgkmcnt(11)
	v_fmac_f32_e32 v24, v8, v44
	v_fmac_f32_e32 v24, v9, v46
	s_waitcnt lgkmcnt(8)
	v_pk_mul_f32 v[20:21], v[80:81], v[156:157] op_sel_hi:[1,0]
	v_pk_mul_f32 v[22:23], v[82:83], v[156:157] op_sel_hi:[1,0]
	v_add_f32_dpp v15, v24, v24 row_ror:8 row_mask:0xf bank_mask:0xf bound_ctrl:1
	v_pk_fma_f32 v[16:17], v[10:11], v[76:77], v[20:21]
	v_pk_fma_f32 v[18:19], v[8:9], v[78:79], v[22:23]
	v_add_f32_dpp v15, v15, v15 row_ror:4 row_mask:0xf bank_mask:0xf bound_ctrl:1
	ds_read_b128 v[116:119], v34 offset:2560
	ds_read_b128 v[120:123], v34 offset:2816
	v_add_f32_dpp v15, v15, v15 row_ror:2 row_mask:0xf bank_mask:0xf bound_ctrl:1
	ds_read_b128 v[124:127], v34 offset:3072
	ds_read_b128 v[128:131], v34 offset:3328
	v_add_f32_dpp v30, v15, v15 row_ror:1 row_mask:0xf bank_mask:0xf bound_ctrl:1
	ds_read_b128 v[132:135], v34 offset:3584
	s_waitcnt lgkmcnt(0)
.Lsc_S_loop:
	s_waitcnt lgkmcnt(1)
	v_pk_fma_f32 v[10:11], v[84:85], v[30:31], v[16:17] op_sel_hi:[1,0,1] neg_lo:[0,1,0] neg_hi:[0,1,0]
	v_pk_fma_f32 v[8:9], v[86:87], v[30:31], v[18:19] op_sel_hi:[1,0,1] neg_lo:[0,1,0] neg_hi:[0,1,0]
	v_pk_mul_f32 v[24:25], v[10:11], v[88:89] op_sel:[0,0] op_sel_hi:[0,1]
	v_pk_fma_f32 v[24:25], v[10:11], v[90:91], v[24:25] op_sel:[1,0,0] op_sel_hi:[1,1,1]
	v_pk_fma_f32 v[24:25], v[8:9], v[92:93], v[24:25] op_sel:[0,0,0] op_sel_hi:[0,1,1]
	v_pk_fma_f32 v[24:25], v[8:9], v[94:95], v[24:25] op_sel:[1,0,0] op_sel_hi:[1,1,1]
	v_pk_mul_f32 v[20:21], v[100:101], v[156:157] op_sel:[0,1] op_sel_hi:[1,1]
	v_pk_mul_f32 v[22:23], v[102:103], v[156:157] op_sel:[0,1] op_sel_hi:[1,1]
	v_add_f32_dpp v15, v24, v24 row_ror:8 row_mask:0xf bank_mask:0xf bound_ctrl:1
	v_pk_fma_f32 v[16:17], v[10:11], v[96:97], v[20:21]
	v_pk_fma_f32 v[18:19], v[8:9], v[98:99], v[22:23]
	v_add_f32_dpp v15, v15, v15 row_ror:4 row_mask:0xf bank_mask:0xf bound_ctrl:1
	v_add_f32_dpp v32, v25, v25 row_ror:8 row_mask:0xf bank_mask:0xf bound_ctrl:1
	ds_read_b128 v[136:139], v34 offset:3840
	v_add_f32_dpp v15, v15, v15 row_ror:2 row_mask:0xf bank_mask:0xf bound_ctrl:1
	ds_read_b128 v[140:143], v34 offset:4096
	ds_read_b128 v[144:147], v34 offset:4352
	v_add_f32_dpp v30, v15, v15 row_ror:1 row_mask:0xf bank_mask:0xf bound_ctrl:1
	ds_read_b128 v[148:151], v34 offset:4608
	ds_read_b128 v[152:155], v34 offset:4864
	ds_read_b128 v[160:163], v35 offset:16
	s_waitcnt lgkmcnt(6)
	v_pk_fma_f32 v[10:11], v[104:105], v[30:31], v[16:17] op_sel_hi:[1,0,1] neg_lo:[0,1,0] neg_hi:[0,1,0]
	v_pk_fma_f32 v[8:9], v[106:107], v[30:31], v[18:19] op_sel_hi:[1,0,1] neg_lo:[0,1,0] neg_hi:[0,1,0]
	v_pk_mul_f32 v[24:25], v[10:11], v[108:109] op_sel:[0,0] op_sel_hi:[0,1]
	v_pk_fma_f32 v[24:25], v[10:11], v[110:111], v[24:25] op_sel:[1,0,0] op_sel_hi:[1,1,1]
	v_pk_fma_f32 v[24:25], v[8:9], v[112:113], v[24:25] op_sel:[0,0,0] op_sel_hi:[0,1,1]
	v_pk_fma_f32 v[24:25], v[8:9], v[114:115], v[24:25] op_sel:[1,0,0] op_sel_hi:[1,1,1]
	v_pk_mul_f32 v[20:21], v[120:121], v[158:159] op_sel_hi:[1,0]
	v_pk_mul_f32 v[22:23], v[122:123], v[158:159] op_sel_hi:[1,0]
	v_add_f32_dpp v15, v24, v24 row_ror:8 row_mask:0xf bank_mask:0xf bound_ctrl:1
	v_pk_fma_f32 v[16:17], v[10:11], v[116:117], v[20:21]
	v_pk_fma_f32 v[18:19], v[8:9], v[118:119], v[22:23]
	v_add_f32_dpp v15, v15, v15 row_ror:4 row_mask:0xf bank_mask:0xf bound_ctrl:1
	v_add_f32_dpp v33, v25, v25 row_ror:8 row_mask:0xf bank_mask:0xf bound_ctrl:1
	ds_read_b128 v[76:79], v34 offset:5120
	v_add_f32_dpp v15, v15, v15 row_ror:2 row_mask:0xf bank_mask:0xf bound_ctrl:1
	ds_read_b128 v[80:83], v34 offset:5376
	ds_read_b128 v[84:87], v34 offset:5632
	v_add_f32_dpp v30, v15, v15 row_ror:1 row_mask:0xf bank_mask:0xf bound_ctrl:1
	ds_read_b128 v[88:91], v34 offset:5888
	ds_read_b128 v[92:95], v34 offset:6144
	ds_write2st64_b32 v37, v32, v33 offset0:0 offset1:2
	s_waitcnt lgkmcnt(6)
	v_pk_fma_f32 v[10:11], v[124:125], v[30:31], v[16:17] op_sel_hi:[1,0,1] neg_lo:[0,1,0] neg_hi:[0,1,0]
	v_pk_fma_f32 v[8:9], v[126:127], v[30:31], v[18:19] op_sel_hi:[1,0,1] neg_lo:[0,1,0] neg_hi:[0,1,0]
	v_pk_mul_f32 v[24:25], v[10:11], v[128:129] op_sel:[0,0] op_sel_hi:[0,1]
	v_pk_fma_f32 v[24:25], v[10:11], v[130:131], v[24:25] op_sel:[1,0,0] op_sel_hi:[1,1,1]
	v_pk_fma_f32 v[24:25], v[8:9], v[132:133], v[24:25] op_sel:[0,0,0] op_sel_hi:[0,1,1]
	v_pk_fma_f32 v[24:25], v[8:9], v[134:135], v[24:25] op_sel:[1,0,0] op_sel_hi:[1,1,1]
	v_pk_mul_f32 v[20:21], v[140:141], v[158:159] op_sel:[0,1] op_sel_hi:[1,1]
	v_pk_mul_f32 v[22:23], v[142:143], v[158:159] op_sel:[0,1] op_sel_hi:[1,1]
	v_add_f32_dpp v15, v24, v24 row_ror:8 row_mask:0xf bank_mask:0xf bound_ctrl:1
	v_pk_fma_f32 v[16:17], v[10:11], v[136:137], v[20:21]
	v_pk_fma_f32 v[18:19], v[8:9], v[138:139], v[22:23]
	v_add_f32_dpp v15, v15, v15 row_ror:4 row_mask:0xf bank_mask:0xf bound_ctrl:1
	v_add_f32_dpp v32, v25, v25 row_ror:8 row_mask:0xf bank_mask:0xf bound_ctrl:1
	ds_read_b128 v[96:99], v34 offset:6400
	v_add_f32_dpp v15, v15, v15 row_ror:2 row_mask:0xf bank_mask:0xf bound_ctrl:1
	ds_read_b128 v[100:103], v34 offset:6656
	ds_read_b128 v[104:107], v34 offset:6912
	v_add_f32_dpp v30, v15, v15 row_ror:1 row_mask:0xf bank_mask:0xf bound_ctrl:1
	ds_read_b128 v[108:111], v34 offset:7168
	ds_read_b128 v[112:115], v34 offset:7424
	s_waitcnt lgkmcnt(5)
	v_pk_fma_f32 v[10:11], v[144:145], v[30:31], v[16:17] op_sel_hi:[1,0,1] neg_lo:[0,1,0] neg_hi:[0,1,0]
	v_pk_fma_f32 v[8:9], v[146:147], v[30:31], v[18:19] op_sel_hi:[1,0,1] neg_lo:[0,1,0] neg_hi:[0,1,0]
	v_pk_mul_f32 v[24:25], v[10:11], v[148:149] op_sel:[0,0] op_sel_hi:[0,1]
	v_pk_fma_f32 v[24:25], v[10:11], v[150:151], v[24:25] op_sel:[1,0,0] op_sel_hi:[1,1,1]
	v_pk_fma_f32 v[24:25], v[8:9], v[152:153], v[24:25] op_sel:[0,0,0] op_sel_hi:[0,1,1]
	v_pk_fma_f32 v[24:25], v[8:9], v[154:155], v[24:25] op_sel:[1,0,0] op_sel_hi:[1,1,1]
	v_pk_mul_f32 v[20:21], v[80:81], v[160:161] op_sel_hi:[1,0]
	v_pk_mul_f32 v[22:23], v[82:83], v[160:161] op_sel_hi:[1,0]
	v_add_f32_dpp v15, v24, v24 row_ror:8 row_mask:0xf bank_mask:0xf bound_ctrl:1
	v_pk_fma_f32 v[16:17], v[10:11], v[76:77], v[20:21]
	v_pk_fma_f32 v[18:19], v[8:9], v[78:79], v[22:23]
	v_add_f32_dpp v15, v15, v15 row_ror:4 row_mask:0xf bank_mask:0xf bound_ctrl:1
	v_add_f32_dpp v33, v25, v25 row_ror:8 row_mask:0xf bank_mask:0xf bound_ctrl:1
	ds_read_b128 v[116:119], v34 offset:7680
	v_add_f32_dpp v15, v15, v15 row_ror:2 row_mask:0xf bank_mask:0xf bound_ctrl:1
	ds_read_b128 v[120:123], v34 offset:7936
	ds_read_b128 v[124:127], v34 offset:8192
	v_add_f32_dpp v30, v15, v15 row_ror:1 row_mask:0xf bank_mask:0xf bound_ctrl:1
	ds_read_b128 v[128:131], v34 offset:8448
	ds_read_b128 v[132:135], v34 offset:8704
	ds_write2st64_b32 v37, v32, v33 offset0:4 offset1:6
	s_waitcnt lgkmcnt(6)
	v_pk_fma_f32 v[10:11], v[84:85], v[30:31], v[16:17] op_sel_hi:[1,0,1] neg_lo:[0,1,0] neg_hi:[0,1,0]
	v_pk_fma_f32 v[8:9], v[86:87], v[30:31], v[18:19] op_sel_hi:[1,0,1] neg_lo:[0,1,0] neg_hi:[0,1,0]
	v_pk_mul_f32 v[24:25], v[10:11], v[88:89] op_sel:[0,0] op_sel_hi:[0,1]
	v_pk_fma_f32 v[24:25], v[10:11], v[90:91], v[24:25] op_sel:[1,0,0] op_sel_hi:[1,1,1]
	v_pk_fma_f32 v[24:25], v[8:9], v[92:93], v[24:25] op_sel:[0,0,0] op_sel_hi:[0,1,1]
	v_pk_fma_f32 v[24:25], v[8:9], v[94:95], v[24:25] op_sel:[1,0,0] op_sel_hi:[1,1,1]
	v_pk_mul_f32 v[20:21], v[100:101], v[160:161] op_sel:[0,1] op_sel_hi:[1,1]
	v_pk_mul_f32 v[22:23], v[102:103], v[160:161] op_sel:[0,1] op_sel_hi:[1,1]
	v_add_f32_dpp v15, v24, v24 row_ror:8 row_mask:0xf bank_mask:0xf bound_ctrl:1
	v_pk_fma_f32 v[16:17], v[10:11], v[96:97], v[20:21]
	v_pk_fma_f32 v[18:19], v[8:9], v[98:99], v[22:23]
	v_add_f32_dpp v15, v15, v15 row_ror:4 row_mask:0xf bank_mask:0xf bound_ctrl:1
	v_add_f32_dpp v32, v25, v25 row_ror:8 row_mask:0xf bank_mask:0xf bound_ctrl:1
	ds_read_b128 v[136:139], v34 offset:8960
	v_add_f32_dpp v15, v15, v15 row_ror:2 row_mask:0xf bank_mask:0xf bound_ctrl:1
	ds_read_b128 v[140:143], v34 offset:9216
	ds_read_b128 v[144:147], v34 offset:9472
	v_add_f32_dpp v30, v15, v15 row_ror:1 row_mask:0xf bank_mask:0xf bound_ctrl:1
	ds_read_b128 v[148:151], v34 offset:9728
	ds_read_b128 v[152:155], v34 offset:9984
	ds_read_b128 v[156:159], v35 offset:32
	s_waitcnt lgkmcnt(6)
	v_pk_fma_f32 v[10:11], v[104:105], v[30:31], v[16:17] op_sel_hi:[1,0,1] neg_lo:[0,1,0] neg_hi:[0,1,0]
	v_pk_fma_f32 v[8:9], v[106:107], v[30:31], v[18:19] op_sel_hi:[1,0,1] neg_lo:[0,1,0] neg_hi:[0,1,0]
	v_pk_mul_f32 v[24:25], v[10:11], v[108:109] op_sel:[0,0] op_sel_hi:[0,1]
	v_pk_fma_f32 v[24:25], v[10:11], v[110:111], v[24:25] op_sel:[1,0,0] op_sel_hi:[1,1,1]
	v_pk_fma_f32 v[24:25], v[8:9], v[112:113], v[24:25] op_sel:[0,0,0] op_sel_hi:[0,1,1]
	v_pk_fma_f32 v[24:25], v[8:9], v[114:115], v[24:25] op_sel:[1,0,0] op_sel_hi:[1,1,1]
	v_pk_mul_f32 v[20:21], v[120:121], v[162:163] op_sel_hi:[1,0]
	v_pk_mul_f32 v[22:23], v[122:123], v[162:163] op_sel_hi:[1,0]
	v_add_f32_dpp v15, v24, v24 row_ror:8 row_mask:0xf bank_mask:0xf bound_ctrl:1
	v_pk_fma_f32 v[16:17], v[10:11], v[116:117], v[20:21]
	v_pk_fma_f32 v[18:19], v[8:9], v[118:119], v[22:23]
	v_add_f32_dpp v15, v15, v15 row_ror:4 row_mask:0xf bank_mask:0xf bound_ctrl:1
	v_add_f32_dpp v33, v25, v25 row_ror:8 row_mask:0xf bank_mask:0xf bound_ctrl:1
	ds_read_b128 v[76:79], v34 offset:10240
	v_add_f32_dpp v15, v15, v15 row_ror:2 row_mask:0xf bank_mask:0xf bound_ctrl:1
	ds_read_b128 v[80:83], v34 offset:10496
	ds_read_b128 v[84:87], v34 offset:10752
	v_add_f32_dpp v30, v15, v15 row_ror:1 row_mask:0xf bank_mask:0xf bound_ctrl:1
	ds_read_b128 v[88:91], v34 offset:11008
	ds_read_b128 v[92:95], v34 offset:11264
	ds_write2st64_b32 v37, v32, v33 offset0:8 offset1:10
	s_waitcnt lgkmcnt(6)
	v_pk_fma_f32 v[10:11], v[124:125], v[30:31], v[16:17] op_sel_hi:[1,0,1] neg_lo:[0,1,0] neg_hi:[0,1,0]
	v_pk_fma_f32 v[8:9], v[126:127], v[30:31], v[18:19] op_sel_hi:[1,0,1] neg_lo:[0,1,0] neg_hi:[0,1,0]
	v_pk_mul_f32 v[24:25], v[10:11], v[128:129] op_sel:[0,0] op_sel_hi:[0,1]
	v_pk_fma_f32 v[24:25], v[10:11], v[130:131], v[24:25] op_sel:[1,0,0] op_sel_hi:[1,1,1]
	v_pk_fma_f32 v[24:25], v[8:9], v[132:133], v[24:25] op_sel:[0,0,0] op_sel_hi:[0,1,1]
	v_pk_fma_f32 v[24:25], v[8:9], v[134:135], v[24:25] op_sel:[1,0,0] op_sel_hi:[1,1,1]
	v_pk_mul_f32 v[20:21], v[140:141], v[162:163] op_sel:[0,1] op_sel_hi:[1,1]
	v_pk_mul_f32 v[22:23], v[142:143], v[162:163] op_sel:[0,1] op_sel_hi:[1,1]
	v_add_f32_dpp v15, v24, v24 row_ror:8 row_mask:0xf bank_mask:0xf bound_ctrl:1
	v_pk_fma_f32 v[16:17], v[10:11], v[136:137], v[20:21]
	v_pk_fma_f32 v[18:19], v[8:9], v[138:139], v[22:23]
	v_add_f32_dpp v15, v15, v15 row_ror:4 row_mask:0xf bank_mask:0xf bound_ctrl:1
	v_add_f32_dpp v32, v25, v25 row_ror:8 row_mask:0xf bank_mask:0xf bound_ctrl:1
	ds_read_b128 v[96:99], v34 offset:11520
	v_add_f32_dpp v15, v15, v15 row_ror:2 row_mask:0xf bank_mask:0xf bound_ctrl:1
	ds_read_b128 v[100:103], v34 offset:11776
	ds_read_b128 v[104:107], v34 offset:12032
	v_add_f32_dpp v30, v15, v15 row_ror:1 row_mask:0xf bank_mask:0xf bound_ctrl:1
	ds_read_b128 v[108:111], v34 offset:12288
	ds_read_b128 v[112:115], v34 offset:12544
	s_waitcnt lgkmcnt(5)
	v_pk_fma_f32 v[10:11], v[144:145], v[30:31], v[16:17] op_sel_hi:[1,0,1] neg_lo:[0,1,0] neg_hi:[0,1,0]
	v_pk_fma_f32 v[8:9], v[146:147], v[30:31], v[18:19] op_sel_hi:[1,0,1] neg_lo:[0,1,0] neg_hi:[0,1,0]
	v_pk_mul_f32 v[24:25], v[10:11], v[148:149] op_sel:[0,0] op_sel_hi:[0,1]
	v_pk_fma_f32 v[24:25], v[10:11], v[150:151], v[24:25] op_sel:[1,0,0] op_sel_hi:[1,1,1]
	v_pk_fma_f32 v[24:25], v[8:9], v[152:153], v[24:25] op_sel:[0,0,0] op_sel_hi:[0,1,1]
	v_pk_fma_f32 v[24:25], v[8:9], v[154:155], v[24:25] op_sel:[1,0,0] op_sel_hi:[1,1,1]
	v_pk_mul_f32 v[20:21], v[80:81], v[156:157] op_sel_hi:[1,0]
	v_pk_mul_f32 v[22:23], v[82:83], v[156:157] op_sel_hi:[1,0]
	v_add_f32_dpp v15, v24, v24 row_ror:8 row_mask:0xf bank_mask:0xf bound_ctrl:1
	v_pk_fma_f32 v[16:17], v[10:11], v[76:77], v[20:21]
	v_pk_fma_f32 v[18:19], v[8:9], v[78:79], v[22:23]
	v_add_f32_dpp v15, v15, v15 row_ror:4 row_mask:0xf bank_mask:0xf bound_ctrl:1
	v_add_f32_dpp v33, v25, v25 row_ror:8 row_mask:0xf bank_mask:0xf bound_ctrl:1
	ds_read_b128 v[116:119], v34 offset:12800
	v_add_f32_dpp v15, v15, v15 row_ror:2 row_mask:0xf bank_mask:0xf bound_ctrl:1
	ds_read_b128 v[120:123], v34 offset:13056
	ds_read_b128 v[124:127], v34 offset:13312
	v_add_f32_dpp v30, v15, v15 row_ror:1 row_mask:0xf bank_mask:0xf bound_ctrl:1
	ds_read_b128 v[128:131], v34 offset:13568
	ds_read_b128 v[132:135], v34 offset:13824
	ds_write2st64_b32 v37, v32, v33 offset0:12 offset1:14
	s_waitcnt lgkmcnt(6)
	v_pk_fma_f32 v[10:11], v[84:85], v[30:31], v[16:17] op_sel_hi:[1,0,1] neg_lo:[0,1,0] neg_hi:[0,1,0]
	v_pk_fma_f32 v[8:9], v[86:87], v[30:31], v[18:19] op_sel_hi:[1,0,1] neg_lo:[0,1,0] neg_hi:[0,1,0]
	v_pk_mul_f32 v[24:25], v[10:11], v[88:89] op_sel:[0,0] op_sel_hi:[0,1]
	v_pk_fma_f32 v[24:25], v[10:11], v[90:91], v[24:25] op_sel:[1,0,0] op_sel_hi:[1,1,1]
	v_pk_fma_f32 v[24:25], v[8:9], v[92:93], v[24:25] op_sel:[0,0,0] op_sel_hi:[0,1,1]
	v_pk_fma_f32 v[24:25], v[8:9], v[94:95], v[24:25] op_sel:[1,0,0] op_sel_hi:[1,1,1]
	v_pk_mul_f32 v[20:21], v[100:101], v[156:157] op_sel:[0,1] op_sel_hi:[1,1]
	v_pk_mul_f32 v[22:23], v[102:103], v[156:157] op_sel:[0,1] op_sel_hi:[1,1]
	v_add_f32_dpp v15, v24, v24 row_ror:8 row_mask:0xf bank_mask:0xf bound_ctrl:1
	v_pk_fma_f32 v[16:17], v[10:11], v[96:97], v[20:21]
	v_pk_fma_f32 v[18:19], v[8:9], v[98:99], v[22:23]
	v_add_f32_dpp v15, v15, v15 row_ror:4 row_mask:0xf bank_mask:0xf bound_ctrl:1
	v_add_f32_dpp v32, v25, v25 row_ror:8 row_mask:0xf bank_mask:0xf bound_ctrl:1
	ds_read_b128 v[136:139], v34 offset:14080
	v_add_f32_dpp v15, v15, v15 row_ror:2 row_mask:0xf bank_mask:0xf bound_ctrl:1
	ds_read_b128 v[140:143], v34 offset:14336
	ds_read_b128 v[144:147], v34 offset:14592
	v_add_f32_dpp v30, v15, v15 row_ror:1 row_mask:0xf bank_mask:0xf bound_ctrl:1
	ds_read_b128 v[148:151], v34 offset:14848
	ds_read_b128 v[152:155], v34 offset:15104
	ds_read_b128 v[160:163], v35 offset:48
	s_waitcnt lgkmcnt(6)
	v_pk_fma_f32 v[10:11], v[104:105], v[30:31], v[16:17] op_sel_hi:[1,0,1] neg_lo:[0,1,0] neg_hi:[0,1,0]
	v_pk_fma_f32 v[8:9], v[106:107], v[30:31], v[18:19] op_sel_hi:[1,0,1] neg_lo:[0,1,0] neg_hi:[0,1,0]
	v_pk_mul_f32 v[24:25], v[10:11], v[108:109] op_sel:[0,0] op_sel_hi:[0,1]
	v_pk_fma_f32 v[24:25], v[10:11], v[110:111], v[24:25] op_sel:[1,0,0] op_sel_hi:[1,1,1]
	v_pk_fma_f32 v[24:25], v[8:9], v[112:113], v[24:25] op_sel:[0,0,0] op_sel_hi:[0,1,1]
	v_pk_fma_f32 v[24:25], v[8:9], v[114:115], v[24:25] op_sel:[1,0,0] op_sel_hi:[1,1,1]
	v_pk_mul_f32 v[20:21], v[120:121], v[158:159] op_sel_hi:[1,0]
	v_pk_mul_f32 v[22:23], v[122:123], v[158:159] op_sel_hi:[1,0]
	v_add_f32_dpp v15, v24, v24 row_ror:8 row_mask:0xf bank_mask:0xf bound_ctrl:1
	v_pk_fma_f32 v[16:17], v[10:11], v[116:117], v[20:21]
	v_pk_fma_f32 v[18:19], v[8:9], v[118:119], v[22:23]
	v_add_f32_dpp v15, v15, v15 row_ror:4 row_mask:0xf bank_mask:0xf bound_ctrl:1
	v_add_f32_dpp v33, v25, v25 row_ror:8 row_mask:0xf bank_mask:0xf bound_ctrl:1
	ds_read_b128 v[76:79], v34 offset:15360
	v_add_f32_dpp v15, v15, v15 row_ror:2 row_mask:0xf bank_mask:0xf bound_ctrl:1
	ds_read_b128 v[80:83], v34 offset:15616
	ds_read_b128 v[84:87], v34 offset:15872
	v_add_f32_dpp v30, v15, v15 row_ror:1 row_mask:0xf bank_mask:0xf bound_ctrl:1
	ds_read_b128 v[88:91], v34 offset:16128
	ds_read_b128 v[92:95], v34 offset:16384
	ds_write2st64_b32 v37, v32, v33 offset0:16 offset1:18
	s_waitcnt lgkmcnt(6)
	v_pk_fma_f32 v[10:11], v[124:125], v[30:31], v[16:17] op_sel_hi:[1,0,1] neg_lo:[0,1,0] neg_hi:[0,1,0]
	v_pk_fma_f32 v[8:9], v[126:127], v[30:31], v[18:19] op_sel_hi:[1,0,1] neg_lo:[0,1,0] neg_hi:[0,1,0]
	v_pk_mul_f32 v[24:25], v[10:11], v[128:129] op_sel:[0,0] op_sel_hi:[0,1]
	v_pk_fma_f32 v[24:25], v[10:11], v[130:131], v[24:25] op_sel:[1,0,0] op_sel_hi:[1,1,1]
	v_pk_fma_f32 v[24:25], v[8:9], v[132:133], v[24:25] op_sel:[0,0,0] op_sel_hi:[0,1,1]
	v_pk_fma_f32 v[24:25], v[8:9], v[134:135], v[24:25] op_sel:[1,0,0] op_sel_hi:[1,1,1]
	v_pk_mul_f32 v[20:21], v[140:141], v[158:159] op_sel:[0,1] op_sel_hi:[1,1]
	v_pk_mul_f32 v[22:23], v[142:143], v[158:159] op_sel:[0,1] op_sel_hi:[1,1]
	v_add_f32_dpp v15, v24, v24 row_ror:8 row_mask:0xf bank_mask:0xf bound_ctrl:1
	v_pk_fma_f32 v[16:17], v[10:11], v[136:137], v[20:21]
	v_pk_fma_f32 v[18:19], v[8:9], v[138:139], v[22:23]
	v_add_f32_dpp v15, v15, v15 row_ror:4 row_mask:0xf bank_mask:0xf bound_ctrl:1
	v_add_f32_dpp v32, v25, v25 row_ror:8 row_mask:0xf bank_mask:0xf bound_ctrl:1
	ds_read_b128 v[96:99], v34 offset:16640
	v_add_f32_dpp v15, v15, v15 row_ror:2 row_mask:0xf bank_mask:0xf bound_ctrl:1
	ds_read_b128 v[100:103], v34 offset:16896
	ds_read_b128 v[104:107], v34 offset:17152
	v_add_f32_dpp v30, v15, v15 row_ror:1 row_mask:0xf bank_mask:0xf bound_ctrl:1
	ds_read_b128 v[108:111], v34 offset:17408
	ds_read_b128 v[112:115], v34 offset:17664
	s_waitcnt lgkmcnt(5)
	v_pk_fma_f32 v[10:11], v[144:145], v[30:31], v[16:17] op_sel_hi:[1,0,1] neg_lo:[0,1,0] neg_hi:[0,1,0]
	v_pk_fma_f32 v[8:9], v[146:147], v[30:31], v[18:19] op_sel_hi:[1,0,1] neg_lo:[0,1,0] neg_hi:[0,1,0]
	v_pk_mul_f32 v[24:25], v[10:11], v[148:149] op_sel:[0,0] op_sel_hi:[0,1]
	v_pk_fma_f32 v[24:25], v[10:11], v[150:151], v[24:25] op_sel:[1,0,0] op_sel_hi:[1,1,1]
	v_pk_fma_f32 v[24:25], v[8:9], v[152:153], v[24:25] op_sel:[0,0,0] op_sel_hi:[0,1,1]
	v_pk_fma_f32 v[24:25], v[8:9], v[154:155], v[24:25] op_sel:[1,0,0] op_sel_hi:[1,1,1]
	v_pk_mul_f32 v[20:21], v[80:81], v[160:161] op_sel_hi:[1,0]
	v_pk_mul_f32 v[22:23], v[82:83], v[160:161] op_sel_hi:[1,0]
	v_add_f32_dpp v15, v24, v24 row_ror:8 row_mask:0xf bank_mask:0xf bound_ctrl:1
	v_pk_fma_f32 v[16:17], v[10:11], v[76:77], v[20:21]
	v_pk_fma_f32 v[18:19], v[8:9], v[78:79], v[22:23]
	v_add_f32_dpp v15, v15, v15 row_ror:4 row_mask:0xf bank_mask:0xf bound_ctrl:1
	v_add_f32_dpp v33, v25, v25 row_ror:8 row_mask:0xf bank_mask:0xf bound_ctrl:1
	ds_read_b128 v[116:119], v34 offset:17920
	v_add_f32_dpp v15, v15, v15 row_ror:2 row_mask:0xf bank_mask:0xf bound_ctrl:1
	ds_read_b128 v[120:123], v34 offset:18176
	ds_read_b128 v[124:127], v34 offset:18432
	v_add_f32_dpp v30, v15, v15 row_ror:1 row_mask:0xf bank_mask:0xf bound_ctrl:1
	ds_read_b128 v[128:131], v34 offset:18688
	ds_read_b128 v[132:135], v34 offset:18944
	ds_write2st64_b32 v37, v32, v33 offset0:20 offset1:22
	s_waitcnt lgkmcnt(6)
	v_pk_fma_f32 v[10:11], v[84:85], v[30:31], v[16:17] op_sel_hi:[1,0,1] neg_lo:[0,1,0] neg_hi:[0,1,0]
	v_pk_fma_f32 v[8:9], v[86:87], v[30:31], v[18:19] op_sel_hi:[1,0,1] neg_lo:[0,1,0] neg_hi:[0,1,0]
	v_pk_mul_f32 v[24:25], v[10:11], v[88:89] op_sel:[0,0] op_sel_hi:[0,1]
	v_pk_fma_f32 v[24:25], v[10:11], v[90:91], v[24:25] op_sel:[1,0,0] op_sel_hi:[1,1,1]
	v_pk_fma_f32 v[24:25], v[8:9], v[92:93], v[24:25] op_sel:[0,0,0] op_sel_hi:[0,1,1]
	v_pk_fma_f32 v[24:25], v[8:9], v[94:95], v[24:25] op_sel:[1,0,0] op_sel_hi:[1,1,1]
	v_pk_mul_f32 v[20:21], v[100:101], v[160:161] op_sel:[0,1] op_sel_hi:[1,1]
	v_pk_mul_f32 v[22:23], v[102:103], v[160:161] op_sel:[0,1] op_sel_hi:[1,1]
	v_add_f32_dpp v15, v24, v24 row_ror:8 row_mask:0xf bank_mask:0xf bound_ctrl:1
	v_pk_fma_f32 v[16:17], v[10:11], v[96:97], v[20:21]
	v_pk_fma_f32 v[18:19], v[8:9], v[98:99], v[22:23]
	v_add_f32_dpp v15, v15, v15 row_ror:4 row_mask:0xf bank_mask:0xf bound_ctrl:1
	v_add_f32_dpp v32, v25, v25 row_ror:8 row_mask:0xf bank_mask:0xf bound_ctrl:1
	ds_read_b128 v[136:139], v34 offset:19200
	v_add_f32_dpp v15, v15, v15 row_ror:2 row_mask:0xf bank_mask:0xf bound_ctrl:1
	ds_read_b128 v[140:143], v34 offset:19456
	ds_read_b128 v[144:147], v34 offset:19712
	v_add_f32_dpp v30, v15, v15 row_ror:1 row_mask:0xf bank_mask:0xf bound_ctrl:1
	ds_read_b128 v[148:151], v34 offset:19968
	ds_read_b128 v[152:155], v34 offset:20224
	ds_read_b128 v[156:159], v35 offset:64
	s_waitcnt lgkmcnt(6)
	v_pk_fma_f32 v[10:11], v[104:105], v[30:31], v[16:17] op_sel_hi:[1,0,1] neg_lo:[0,1,0] neg_hi:[0,1,0]
	v_pk_fma_f32 v[8:9], v[106:107], v[30:31], v[18:19] op_sel_hi:[1,0,1] neg_lo:[0,1,0] neg_hi:[0,1,0]
	v_pk_mul_f32 v[24:25], v[10:11], v[108:109] op_sel:[0,0] op_sel_hi:[0,1]
	v_pk_fma_f32 v[24:25], v[10:11], v[110:111], v[24:25] op_sel:[1,0,0] op_sel_hi:[1,1,1]
	v_pk_fma_f32 v[24:25], v[8:9], v[112:113], v[24:25] op_sel:[0,0,0] op_sel_hi:[0,1,1]
	v_pk_fma_f32 v[24:25], v[8:9], v[114:115], v[24:25] op_sel:[1,0,0] op_sel_hi:[1,1,1]
	v_pk_mul_f32 v[20:21], v[120:121], v[162:163] op_sel_hi:[1,0]
	v_pk_mul_f32 v[22:23], v[122:123], v[162:163] op_sel_hi:[1,0]
	v_add_f32_dpp v15, v24, v24 row_ror:8 row_mask:0xf bank_mask:0xf bound_ctrl:1
	v_pk_fma_f32 v[16:17], v[10:11], v[116:117], v[20:21]
	v_pk_fma_f32 v[18:19], v[8:9], v[118:119], v[22:23]
	v_add_f32_dpp v15, v15, v15 row_ror:4 row_mask:0xf bank_mask:0xf bound_ctrl:1
	v_add_f32_dpp v33, v25, v25 row_ror:8 row_mask:0xf bank_mask:0xf bound_ctrl:1
	ds_read_b128 v[76:79], v34 offset:20480
	v_add_f32_dpp v15, v15, v15 row_ror:2 row_mask:0xf bank_mask:0xf bound_ctrl:1
	ds_read_b128 v[80:83], v34 offset:20736
	ds_read_b128 v[84:87], v34 offset:20992
	v_add_f32_dpp v30, v15, v15 row_ror:1 row_mask:0xf bank_mask:0xf bound_ctrl:1
	ds_read_b128 v[88:91], v34 offset:21248
	ds_read_b128 v[92:95], v34 offset:21504
	ds_write2st64_b32 v37, v32, v33 offset0:24 offset1:26
	s_waitcnt lgkmcnt(6)
	v_pk_fma_f32 v[10:11], v[124:125], v[30:31], v[16:17] op_sel_hi:[1,0,1] neg_lo:[0,1,0] neg_hi:[0,1,0]
	v_pk_fma_f32 v[8:9], v[126:127], v[30:31], v[18:19] op_sel_hi:[1,0,1] neg_lo:[0,1,0] neg_hi:[0,1,0]
	v_pk_mul_f32 v[24:25], v[10:11], v[128:129] op_sel:[0,0] op_sel_hi:[0,1]
	v_pk_fma_f32 v[24:25], v[10:11], v[130:131], v[24:25] op_sel:[1,0,0] op_sel_hi:[1,1,1]
	v_pk_fma_f32 v[24:25], v[8:9], v[132:133], v[24:25] op_sel:[0,0,0] op_sel_hi:[0,1,1]
	v_pk_fma_f32 v[24:25], v[8:9], v[134:135], v[24:25] op_sel:[1,0,0] op_sel_hi:[1,1,1]
	v_pk_mul_f32 v[20:21], v[140:141], v[162:163] op_sel:[0,1] op_sel_hi:[1,1]
	v_pk_mul_f32 v[22:23], v[142:143], v[162:163] op_sel:[0,1] op_sel_hi:[1,1]
	v_add_f32_dpp v15, v24, v24 row_ror:8 row_mask:0xf bank_mask:0xf bound_ctrl:1
	v_pk_fma_f32 v[16:17], v[10:11], v[136:137], v[20:21]
	v_pk_fma_f32 v[18:19], v[8:9], v[138:139], v[22:23]
	v_add_f32_dpp v15, v15, v15 row_ror:4 row_mask:0xf bank_mask:0xf bound_ctrl:1
	v_add_f32_dpp v32, v25, v25 row_ror:8 row_mask:0xf bank_mask:0xf bound_ctrl:1
	ds_read_b128 v[96:99], v34 offset:21760
	v_add_f32_dpp v15, v15, v15 row_ror:2 row_mask:0xf bank_mask:0xf bound_ctrl:1
	ds_read_b128 v[100:103], v34 offset:22016
	ds_read_b128 v[104:107], v34 offset:22272
	v_add_f32_dpp v30, v15, v15 row_ror:1 row_mask:0xf bank_mask:0xf bound_ctrl:1
	ds_read_b128 v[108:111], v34 offset:22528
	ds_read_b128 v[112:115], v34 offset:22784
	s_waitcnt lgkmcnt(5)
	v_pk_fma_f32 v[10:11], v[144:145], v[30:31], v[16:17] op_sel_hi:[1,0,1] neg_lo:[0,1,0] neg_hi:[0,1,0]
	v_pk_fma_f32 v[8:9], v[146:147], v[30:31], v[18:19] op_sel_hi:[1,0,1] neg_lo:[0,1,0] neg_hi:[0,1,0]
	v_pk_mul_f32 v[24:25], v[10:11], v[148:149] op_sel:[0,0] op_sel_hi:[0,1]
	v_pk_fma_f32 v[24:25], v[10:11], v[150:151], v[24:25] op_sel:[1,0,0] op_sel_hi:[1,1,1]
	v_pk_fma_f32 v[24:25], v[8:9], v[152:153], v[24:25] op_sel:[0,0,0] op_sel_hi:[0,1,1]
	v_pk_fma_f32 v[24:25], v[8:9], v[154:155], v[24:25] op_sel:[1,0,0] op_sel_hi:[1,1,1]
	v_pk_mul_f32 v[20:21], v[80:81], v[156:157] op_sel_hi:[1,0]
	v_pk_mul_f32 v[22:23], v[82:83], v[156:157] op_sel_hi:[1,0]
	v_add_f32_dpp v15, v24, v24 row_ror:8 row_mask:0xf bank_mask:0xf bound_ctrl:1
	v_pk_fma_f32 v[16:17], v[10:11], v[76:77], v[20:21]
	v_pk_fma_f32 v[18:19], v[8:9], v[78:79], v[22:23]
	v_add_f32_dpp v15, v15, v15 row_ror:4 row_mask:0xf bank_mask:0xf bound_ctrl:1
	v_add_f32_dpp v33, v25, v25 row_ror:8 row_mask:0xf bank_mask:0xf bound_ctrl:1
	ds_read_b128 v[116:119], v34 offset:23040
	v_add_f32_dpp v15, v15, v15 row_ror:2 row_mask:0xf bank_mask:0xf bound_ctrl:1
	ds_read_b128 v[120:123], v34 offset:23296
	ds_read_b128 v[124:127], v34 offset:23552
	v_add_f32_dpp v30, v15, v15 row_ror:1 row_mask:0xf bank_mask:0xf bound_ctrl:1
	ds_read_b128 v[128:131], v34 offset:23808
	ds_read_b128 v[132:135], v34 offset:24064
	ds_write2st64_b32 v37, v32, v33 offset0:28 offset1:30
	s_waitcnt lgkmcnt(6)
	v_pk_fma_f32 v[10:11], v[84:85], v[30:31], v[16:17] op_sel_hi:[1,0,1] neg_lo:[0,1,0] neg_hi:[0,1,0]
	v_pk_fma_f32 v[8:9], v[86:87], v[30:31], v[18:19] op_sel_hi:[1,0,1] neg_lo:[0,1,0] neg_hi:[0,1,0]
	v_pk_mul_f32 v[24:25], v[10:11], v[88:89] op_sel:[0,0] op_sel_hi:[0,1]
	v_pk_fma_f32 v[24:25], v[10:11], v[90:91], v[24:25] op_sel:[1,0,0] op_sel_hi:[1,1,1]
	v_pk_fma_f32 v[24:25], v[8:9], v[92:93], v[24:25] op_sel:[0,0,0] op_sel_hi:[0,1,1]
	v_pk_fma_f32 v[24:25], v[8:9], v[94:95], v[24:25] op_sel:[1,0,0] op_sel_hi:[1,1,1]
	v_pk_mul_f32 v[20:21], v[100:101], v[156:157] op_sel:[0,1] op_sel_hi:[1,1]
	v_pk_mul_f32 v[22:23], v[102:103], v[156:157] op_sel:[0,1] op_sel_hi:[1,1]
	v_add_f32_dpp v15, v24, v24 row_ror:8 row_mask:0xf bank_mask:0xf bound_ctrl:1
	v_pk_fma_f32 v[16:17], v[10:11], v[96:97], v[20:21]
	v_pk_fma_f32 v[18:19], v[8:9], v[98:99], v[22:23]
	v_add_f32_dpp v15, v15, v15 row_ror:4 row_mask:0xf bank_mask:0xf bound_ctrl:1
	v_add_f32_dpp v32, v25, v25 row_ror:8 row_mask:0xf bank_mask:0xf bound_ctrl:1
	ds_read_b128 v[136:139], v34 offset:24320
	v_add_f32_dpp v15, v15, v15 row_ror:2 row_mask:0xf bank_mask:0xf bound_ctrl:1
	ds_read_b128 v[140:143], v34 offset:24576
	ds_read_b128 v[144:147], v34 offset:24832
	v_add_f32_dpp v30, v15, v15 row_ror:1 row_mask:0xf bank_mask:0xf bound_ctrl:1
	ds_read_b128 v[148:151], v34 offset:25088
	ds_read_b128 v[152:155], v34 offset:25344
	ds_read_b128 v[160:163], v35 offset:80
	s_waitcnt lgkmcnt(6)
	v_pk_fma_f32 v[10:11], v[104:105], v[30:31], v[16:17] op_sel_hi:[1,0,1] neg_lo:[0,1,0] neg_hi:[0,1,0]
	v_pk_fma_f32 v[8:9], v[106:107], v[30:31], v[18:19] op_sel_hi:[1,0,1] neg_lo:[0,1,0] neg_hi:[0,1,0]
	v_pk_mul_f32 v[24:25], v[10:11], v[108:109] op_sel:[0,0] op_sel_hi:[0,1]
	v_pk_fma_f32 v[24:25], v[10:11], v[110:111], v[24:25] op_sel:[1,0,0] op_sel_hi:[1,1,1]
	v_pk_fma_f32 v[24:25], v[8:9], v[112:113], v[24:25] op_sel:[0,0,0] op_sel_hi:[0,1,1]
	v_pk_fma_f32 v[24:25], v[8:9], v[114:115], v[24:25] op_sel:[1,0,0] op_sel_hi:[1,1,1]
	v_pk_mul_f32 v[20:21], v[120:121], v[158:159] op_sel_hi:[1,0]
	v_pk_mul_f32 v[22:23], v[122:123], v[158:159] op_sel_hi:[1,0]
	v_add_f32_dpp v15, v24, v24 row_ror:8 row_mask:0xf bank_mask:0xf bound_ctrl:1
	v_pk_fma_f32 v[16:17], v[10:11], v[116:117], v[20:21]
	v_pk_fma_f32 v[18:19], v[8:9], v[118:119], v[22:23]
	v_add_f32_dpp v15, v15, v15 row_ror:4 row_mask:0xf bank_mask:0xf bound_ctrl:1
	v_add_f32_dpp v33, v25, v25 row_ror:8 row_mask:0xf bank_mask:0xf bound_ctrl:1
	ds_read_b128 v[76:79], v34 offset:25600
	v_add_f32_dpp v15, v15, v15 row_ror:2 row_mask:0xf bank_mask:0xf bound_ctrl:1
	ds_read_b128 v[80:83], v34 offset:25856
	ds_read_b128 v[84:87], v34 offset:26112
	v_add_f32_dpp v30, v15, v15 row_ror:1 row_mask:0xf bank_mask:0xf bound_ctrl:1
	ds_read_b128 v[88:91], v34 offset:26368
	ds_read_b128 v[92:95], v34 offset:26624
	ds_write2st64_b32 v37, v32, v33 offset0:32 offset1:34
	s_waitcnt lgkmcnt(6)
	v_pk_fma_f32 v[10:11], v[124:125], v[30:31], v[16:17] op_sel_hi:[1,0,1] neg_lo:[0,1,0] neg_hi:[0,1,0]
	v_pk_fma_f32 v[8:9], v[126:127], v[30:31], v[18:19] op_sel_hi:[1,0,1] neg_lo:[0,1,0] neg_hi:[0,1,0]
	v_pk_mul_f32 v[24:25], v[10:11], v[128:129] op_sel:[0,0] op_sel_hi:[0,1]
	v_pk_fma_f32 v[24:25], v[10:11], v[130:131], v[24:25] op_sel:[1,0,0] op_sel_hi:[1,1,1]
	v_pk_fma_f32 v[24:25], v[8:9], v[132:133], v[24:25] op_sel:[0,0,0] op_sel_hi:[0,1,1]
	v_pk_fma_f32 v[24:25], v[8:9], v[134:135], v[24:25] op_sel:[1,0,0] op_sel_hi:[1,1,1]
	v_pk_mul_f32 v[20:21], v[140:141], v[158:159] op_sel:[0,1] op_sel_hi:[1,1]
	v_pk_mul_f32 v[22:23], v[142:143], v[158:159] op_sel:[0,1] op_sel_hi:[1,1]
	v_add_f32_dpp v15, v24, v24 row_ror:8 row_mask:0xf bank_mask:0xf bound_ctrl:1
	v_pk_fma_f32 v[16:17], v[10:11], v[136:137], v[20:21]
	v_pk_fma_f32 v[18:19], v[8:9], v[138:139], v[22:23]
	v_add_f32_dpp v15, v15, v15 row_ror:4 row_mask:0xf bank_mask:0xf bound_ctrl:1
	v_add_f32_dpp v32, v25, v25 row_ror:8 row_mask:0xf bank_mask:0xf bound_ctrl:1
	ds_read_b128 v[96:99], v34 offset:26880
	v_add_f32_dpp v15, v15, v15 row_ror:2 row_mask:0xf bank_mask:0xf bound_ctrl:1
	ds_read_b128 v[100:103], v34 offset:27136
	ds_read_b128 v[104:107], v34 offset:27392
	v_add_f32_dpp v30, v15, v15 row_ror:1 row_mask:0xf bank_mask:0xf bound_ctrl:1
	ds_read_b128 v[108:111], v34 offset:27648
	ds_read_b128 v[112:115], v34 offset:27904
	s_waitcnt lgkmcnt(5)
	v_pk_fma_f32 v[10:11], v[144:145], v[30:31], v[16:17] op_sel_hi:[1,0,1] neg_lo:[0,1,0] neg_hi:[0,1,0]
	v_pk_fma_f32 v[8:9], v[146:147], v[30:31], v[18:19] op_sel_hi:[1,0,1] neg_lo:[0,1,0] neg_hi:[0,1,0]
	v_pk_mul_f32 v[24:25], v[10:11], v[148:149] op_sel:[0,0] op_sel_hi:[0,1]
	v_pk_fma_f32 v[24:25], v[10:11], v[150:151], v[24:25] op_sel:[1,0,0] op_sel_hi:[1,1,1]
	v_pk_fma_f32 v[24:25], v[8:9], v[152:153], v[24:25] op_sel:[0,0,0] op_sel_hi:[0,1,1]
	v_pk_fma_f32 v[24:25], v[8:9], v[154:155], v[24:25] op_sel:[1,0,0] op_sel_hi:[1,1,1]
	v_pk_mul_f32 v[20:21], v[80:81], v[160:161] op_sel_hi:[1,0]
	v_pk_mul_f32 v[22:23], v[82:83], v[160:161] op_sel_hi:[1,0]
	v_add_f32_dpp v15, v24, v24 row_ror:8 row_mask:0xf bank_mask:0xf bound_ctrl:1
	v_pk_fma_f32 v[16:17], v[10:11], v[76:77], v[20:21]
	v_pk_fma_f32 v[18:19], v[8:9], v[78:79], v[22:23]
	v_add_f32_dpp v15, v15, v15 row_ror:4 row_mask:0xf bank_mask:0xf bound_ctrl:1
	v_add_f32_dpp v33, v25, v25 row_ror:8 row_mask:0xf bank_mask:0xf bound_ctrl:1
	ds_read_b128 v[116:119], v34 offset:28160
	v_add_f32_dpp v15, v15, v15 row_ror:2 row_mask:0xf bank_mask:0xf bound_ctrl:1
	ds_read_b128 v[120:123], v34 offset:28416
	ds_read_b128 v[124:127], v34 offset:28672
	v_add_f32_dpp v30, v15, v15 row_ror:1 row_mask:0xf bank_mask:0xf bound_ctrl:1
	ds_read_b128 v[128:131], v34 offset:28928
	ds_read_b128 v[132:135], v34 offset:29184
	ds_write2st64_b32 v37, v32, v33 offset0:36 offset1:38
	s_waitcnt lgkmcnt(6)
	v_pk_fma_f32 v[10:11], v[84:85], v[30:31], v[16:17] op_sel_hi:[1,0,1] neg_lo:[0,1,0] neg_hi:[0,1,0]
	v_pk_fma_f32 v[8:9], v[86:87], v[30:31], v[18:19] op_sel_hi:[1,0,1] neg_lo:[0,1,0] neg_hi:[0,1,0]
	v_pk_mul_f32 v[24:25], v[10:11], v[88:89] op_sel:[0,0] op_sel_hi:[0,1]
	v_pk_fma_f32 v[24:25], v[10:11], v[90:91], v[24:25] op_sel:[1,0,0] op_sel_hi:[1,1,1]
	v_pk_fma_f32 v[24:25], v[8:9], v[92:93], v[24:25] op_sel:[0,0,0] op_sel_hi:[0,1,1]
	v_pk_fma_f32 v[24:25], v[8:9], v[94:95], v[24:25] op_sel:[1,0,0] op_sel_hi:[1,1,1]
	v_pk_mul_f32 v[20:21], v[100:101], v[160:161] op_sel:[0,1] op_sel_hi:[1,1]
	v_pk_mul_f32 v[22:23], v[102:103], v[160:161] op_sel:[0,1] op_sel_hi:[1,1]
	v_add_f32_dpp v15, v24, v24 row_ror:8 row_mask:0xf bank_mask:0xf bound_ctrl:1
	v_pk_fma_f32 v[16:17], v[10:11], v[96:97], v[20:21]
	v_pk_fma_f32 v[18:19], v[8:9], v[98:99], v[22:23]
	v_add_f32_dpp v15, v15, v15 row_ror:4 row_mask:0xf bank_mask:0xf bound_ctrl:1
	v_add_f32_dpp v32, v25, v25 row_ror:8 row_mask:0xf bank_mask:0xf bound_ctrl:1
	ds_read_b128 v[136:139], v34 offset:29440
	v_add_f32_dpp v15, v15, v15 row_ror:2 row_mask:0xf bank_mask:0xf bound_ctrl:1
	ds_read_b128 v[140:143], v34 offset:29696
	ds_read_b128 v[144:147], v34 offset:29952
	v_add_f32_dpp v30, v15, v15 row_ror:1 row_mask:0xf bank_mask:0xf bound_ctrl:1
	ds_read_b128 v[148:151], v34 offset:30208
	ds_read_b128 v[152:155], v34 offset:30464
	ds_read_b128 v[156:159], v35 offset:96
	s_waitcnt lgkmcnt(6)
	v_pk_fma_f32 v[10:11], v[104:105], v[30:31], v[16:17] op_sel_hi:[1,0,1] neg_lo:[0,1,0] neg_hi:[0,1,0]
	v_pk_fma_f32 v[8:9], v[106:107], v[30:31], v[18:19] op_sel_hi:[1,0,1] neg_lo:[0,1,0] neg_hi:[0,1,0]
	v_pk_mul_f32 v[24:25], v[10:11], v[108:109] op_sel:[0,0] op_sel_hi:[0,1]
	v_pk_fma_f32 v[24:25], v[10:11], v[110:111], v[24:25] op_sel:[1,0,0] op_sel_hi:[1,1,1]
	v_pk_fma_f32 v[24:25], v[8:9], v[112:113], v[24:25] op_sel:[0,0,0] op_sel_hi:[0,1,1]
	v_pk_fma_f32 v[24:25], v[8:9], v[114:115], v[24:25] op_sel:[1,0,0] op_sel_hi:[1,1,1]
	v_pk_mul_f32 v[20:21], v[120:121], v[162:163] op_sel_hi:[1,0]
	v_pk_mul_f32 v[22:23], v[122:123], v[162:163] op_sel_hi:[1,0]
	v_add_f32_dpp v15, v24, v24 row_ror:8 row_mask:0xf bank_mask:0xf bound_ctrl:1
	v_pk_fma_f32 v[16:17], v[10:11], v[116:117], v[20:21]
	v_pk_fma_f32 v[18:19], v[8:9], v[118:119], v[22:23]
	v_add_f32_dpp v15, v15, v15 row_ror:4 row_mask:0xf bank_mask:0xf bound_ctrl:1
	v_add_f32_dpp v33, v25, v25 row_ror:8 row_mask:0xf bank_mask:0xf bound_ctrl:1
	ds_read_b128 v[76:79], v34 offset:30720
	v_add_f32_dpp v15, v15, v15 row_ror:2 row_mask:0xf bank_mask:0xf bound_ctrl:1
	ds_read_b128 v[80:83], v34 offset:30976
	ds_read_b128 v[84:87], v34 offset:31232
	v_add_f32_dpp v30, v15, v15 row_ror:1 row_mask:0xf bank_mask:0xf bound_ctrl:1
	ds_read_b128 v[88:91], v34 offset:31488
	ds_read_b128 v[92:95], v34 offset:31744
	ds_write2st64_b32 v37, v32, v33 offset0:40 offset1:42
	s_waitcnt lgkmcnt(6)
	v_pk_fma_f32 v[10:11], v[124:125], v[30:31], v[16:17] op_sel_hi:[1,0,1] neg_lo:[0,1,0] neg_hi:[0,1,0]
	v_pk_fma_f32 v[8:9], v[126:127], v[30:31], v[18:19] op_sel_hi:[1,0,1] neg_lo:[0,1,0] neg_hi:[0,1,0]
	v_pk_mul_f32 v[24:25], v[10:11], v[128:129] op_sel:[0,0] op_sel_hi:[0,1]
	v_pk_fma_f32 v[24:25], v[10:11], v[130:131], v[24:25] op_sel:[1,0,0] op_sel_hi:[1,1,1]
	v_pk_fma_f32 v[24:25], v[8:9], v[132:133], v[24:25] op_sel:[0,0,0] op_sel_hi:[0,1,1]
	v_pk_fma_f32 v[24:25], v[8:9], v[134:135], v[24:25] op_sel:[1,0,0] op_sel_hi:[1,1,1]
	v_pk_mul_f32 v[20:21], v[140:141], v[162:163] op_sel:[0,1] op_sel_hi:[1,1]
	v_pk_mul_f32 v[22:23], v[142:143], v[162:163] op_sel:[0,1] op_sel_hi:[1,1]
	v_add_f32_dpp v15, v24, v24 row_ror:8 row_mask:0xf bank_mask:0xf bound_ctrl:1
	v_pk_fma_f32 v[16:17], v[10:11], v[136:137], v[20:21]
	v_pk_fma_f32 v[18:19], v[8:9], v[138:139], v[22:23]
	v_add_f32_dpp v15, v15, v15 row_ror:4 row_mask:0xf bank_mask:0xf bound_ctrl:1
	v_add_f32_dpp v32, v25, v25 row_ror:8 row_mask:0xf bank_mask:0xf bound_ctrl:1
	ds_read_b128 v[96:99], v34 offset:32000
	v_add_f32_dpp v15, v15, v15 row_ror:2 row_mask:0xf bank_mask:0xf bound_ctrl:1
	ds_read_b128 v[100:103], v34 offset:32256
	ds_read_b128 v[104:107], v34 offset:32512
	v_add_f32_dpp v30, v15, v15 row_ror:1 row_mask:0xf bank_mask:0xf bound_ctrl:1
	ds_read_b128 v[108:111], v34 offset:32768
	ds_read_b128 v[112:115], v34 offset:33024
	s_waitcnt lgkmcnt(5)
	v_pk_fma_f32 v[10:11], v[144:145], v[30:31], v[16:17] op_sel_hi:[1,0,1] neg_lo:[0,1,0] neg_hi:[0,1,0]
	v_pk_fma_f32 v[8:9], v[146:147], v[30:31], v[18:19] op_sel_hi:[1,0,1] neg_lo:[0,1,0] neg_hi:[0,1,0]
	v_pk_mul_f32 v[24:25], v[10:11], v[148:149] op_sel:[0,0] op_sel_hi:[0,1]
	v_pk_fma_f32 v[24:25], v[10:11], v[150:151], v[24:25] op_sel:[1,0,0] op_sel_hi:[1,1,1]
	v_pk_fma_f32 v[24:25], v[8:9], v[152:153], v[24:25] op_sel:[0,0,0] op_sel_hi:[0,1,1]
	v_pk_fma_f32 v[24:25], v[8:9], v[154:155], v[24:25] op_sel:[1,0,0] op_sel_hi:[1,1,1]
	v_pk_mul_f32 v[20:21], v[80:81], v[156:157] op_sel_hi:[1,0]
	v_pk_mul_f32 v[22:23], v[82:83], v[156:157] op_sel_hi:[1,0]
	v_add_f32_dpp v15, v24, v24 row_ror:8 row_mask:0xf bank_mask:0xf bound_ctrl:1
	v_pk_fma_f32 v[16:17], v[10:11], v[76:77], v[20:21]
	v_pk_fma_f32 v[18:19], v[8:9], v[78:79], v[22:23]
	v_add_f32_dpp v15, v15, v15 row_ror:4 row_mask:0xf bank_mask:0xf bound_ctrl:1
	v_add_f32_dpp v33, v25, v25 row_ror:8 row_mask:0xf bank_mask:0xf bound_ctrl:1
	ds_read_b128 v[116:119], v34 offset:33280
	v_add_f32_dpp v15, v15, v15 row_ror:2 row_mask:0xf bank_mask:0xf bound_ctrl:1
	ds_read_b128 v[120:123], v34 offset:33536
	ds_read_b128 v[124:127], v34 offset:33792
	v_add_f32_dpp v30, v15, v15 row_ror:1 row_mask:0xf bank_mask:0xf bound_ctrl:1
	ds_read_b128 v[128:131], v34 offset:34048
	ds_read_b128 v[132:135], v34 offset:34304
	ds_write2st64_b32 v37, v32, v33 offset0:44 offset1:46
	s_waitcnt lgkmcnt(6)
	v_pk_fma_f32 v[10:11], v[84:85], v[30:31], v[16:17] op_sel_hi:[1,0,1] neg_lo:[0,1,0] neg_hi:[0,1,0]
	v_pk_fma_f32 v[8:9], v[86:87], v[30:31], v[18:19] op_sel_hi:[1,0,1] neg_lo:[0,1,0] neg_hi:[0,1,0]
	v_pk_mul_f32 v[24:25], v[10:11], v[88:89] op_sel:[0,0] op_sel_hi:[0,1]
	v_pk_fma_f32 v[24:25], v[10:11], v[90:91], v[24:25] op_sel:[1,0,0] op_sel_hi:[1,1,1]
	v_pk_fma_f32 v[24:25], v[8:9], v[92:93], v[24:25] op_sel:[0,0,0] op_sel_hi:[0,1,1]
	v_pk_fma_f32 v[24:25], v[8:9], v[94:95], v[24:25] op_sel:[1,0,0] op_sel_hi:[1,1,1]
	v_pk_mul_f32 v[20:21], v[100:101], v[156:157] op_sel:[0,1] op_sel_hi:[1,1]
	v_pk_mul_f32 v[22:23], v[102:103], v[156:157] op_sel:[0,1] op_sel_hi:[1,1]
	v_add_f32_dpp v15, v24, v24 row_ror:8 row_mask:0xf bank_mask:0xf bound_ctrl:1
	v_pk_fma_f32 v[16:17], v[10:11], v[96:97], v[20:21]
	v_pk_fma_f32 v[18:19], v[8:9], v[98:99], v[22:23]
	v_add_f32_dpp v15, v15, v15 row_ror:4 row_mask:0xf bank_mask:0xf bound_ctrl:1
	v_add_f32_dpp v32, v25, v25 row_ror:8 row_mask:0xf bank_mask:0xf bound_ctrl:1
	ds_read_b128 v[136:139], v34 offset:34560
	v_add_f32_dpp v15, v15, v15 row_ror:2 row_mask:0xf bank_mask:0xf bound_ctrl:1
	ds_read_b128 v[140:143], v34 offset:34816
	ds_read_b128 v[144:147], v34 offset:35072
	v_add_f32_dpp v30, v15, v15 row_ror:1 row_mask:0xf bank_mask:0xf bound_ctrl:1
	ds_read_b128 v[148:151], v34 offset:35328
	ds_read_b128 v[152:155], v34 offset:35584
	ds_read_b128 v[160:163], v35 offset:112
	s_waitcnt lgkmcnt(6)
	v_pk_fma_f32 v[10:11], v[104:105], v[30:31], v[16:17] op_sel_hi:[1,0,1] neg_lo:[0,1,0] neg_hi:[0,1,0]
	v_pk_fma_f32 v[8:9], v[106:107], v[30:31], v[18:19] op_sel_hi:[1,0,1] neg_lo:[0,1,0] neg_hi:[0,1,0]
	v_pk_mul_f32 v[24:25], v[10:11], v[108:109] op_sel:[0,0] op_sel_hi:[0,1]
	v_pk_fma_f32 v[24:25], v[10:11], v[110:111], v[24:25] op_sel:[1,0,0] op_sel_hi:[1,1,1]
	v_pk_fma_f32 v[24:25], v[8:9], v[112:113], v[24:25] op_sel:[0,0,0] op_sel_hi:[0,1,1]
	v_pk_fma_f32 v[24:25], v[8:9], v[114:115], v[24:25] op_sel:[1,0,0] op_sel_hi:[1,1,1]
	v_pk_mul_f32 v[20:21], v[120:121], v[158:159] op_sel_hi:[1,0]
	v_pk_mul_f32 v[22:23], v[122:123], v[158:159] op_sel_hi:[1,0]
	v_add_f32_dpp v15, v24, v24 row_ror:8 row_mask:0xf bank_mask:0xf bound_ctrl:1
	v_pk_fma_f32 v[16:17], v[10:11], v[116:117], v[20:21]
	v_pk_fma_f32 v[18:19], v[8:9], v[118:119], v[22:23]
	v_add_f32_dpp v15, v15, v15 row_ror:4 row_mask:0xf bank_mask:0xf bound_ctrl:1
	v_add_f32_dpp v33, v25, v25 row_ror:8 row_mask:0xf bank_mask:0xf bound_ctrl:1
	ds_read_b128 v[76:79], v34 offset:35840
	v_add_f32_dpp v15, v15, v15 row_ror:2 row_mask:0xf bank_mask:0xf bound_ctrl:1
	ds_read_b128 v[80:83], v34 offset:36096
	ds_read_b128 v[84:87], v34 offset:36352
	v_add_f32_dpp v30, v15, v15 row_ror:1 row_mask:0xf bank_mask:0xf bound_ctrl:1
	ds_read_b128 v[88:91], v34 offset:36608
	ds_read_b128 v[92:95], v34 offset:36864
	ds_write2st64_b32 v37, v32, v33 offset0:48 offset1:50
	ds_read_b128 v[56:59], v52
	s_waitcnt lgkmcnt(6)
	v_pk_fma_f32 v[10:11], v[124:125], v[30:31], v[16:17] op_sel_hi:[1,0,1] neg_lo:[0,1,0] neg_hi:[0,1,0]
	v_pk_fma_f32 v[8:9], v[126:127], v[30:31], v[18:19] op_sel_hi:[1,0,1] neg_lo:[0,1,0] neg_hi:[0,1,0]
	v_pk_mul_f32 v[24:25], v[10:11], v[128:129] op_sel:[0,0] op_sel_hi:[0,1]
	v_pk_fma_f32 v[24:25], v[10:11], v[130:131], v[24:25] op_sel:[1,0,0] op_sel_hi:[1,1,1]
	v_pk_fma_f32 v[24:25], v[8:9], v[132:133], v[24:25] op_sel:[0,0,0] op_sel_hi:[0,1,1]
	v_pk_fma_f32 v[24:25], v[8:9], v[134:135], v[24:25] op_sel:[1,0,0] op_sel_hi:[1,1,1]
	v_pk_mul_f32 v[20:21], v[140:141], v[158:159] op_sel:[0,1] op_sel_hi:[1,1]
	v_pk_mul_f32 v[22:23], v[142:143], v[158:159] op_sel:[0,1] op_sel_hi:[1,1]
	v_add_f32_dpp v15, v24, v24 row_ror:8 row_mask:0xf bank_mask:0xf bound_ctrl:1
	v_pk_fma_f32 v[16:17], v[10:11], v[136:137], v[20:21]
	v_pk_fma_f32 v[18:19], v[8:9], v[138:139], v[22:23]
	v_add_f32_dpp v15, v15, v15 row_ror:4 row_mask:0xf bank_mask:0xf bound_ctrl:1
	v_add_f32_dpp v32, v25, v25 row_ror:8 row_mask:0xf bank_mask:0xf bound_ctrl:1
	ds_read_b128 v[96:99], v34 offset:37120
	v_add_f32_dpp v15, v15, v15 row_ror:2 row_mask:0xf bank_mask:0xf bound_ctrl:1
	ds_read_b128 v[100:103], v34 offset:37376
	ds_read_b128 v[104:107], v34 offset:37632
	v_add_f32_dpp v30, v15, v15 row_ror:1 row_mask:0xf bank_mask:0xf bound_ctrl:1
	ds_read_b128 v[108:111], v34 offset:37888
	ds_read_b128 v[112:115], v34 offset:38144
	s_waitcnt lgkmcnt(5)
	v_min_u32_e32 v56, v56, v57
	v_min3_u32 v56, v56, v58, v59
	v_pk_fma_f32 v[10:11], v[144:145], v[30:31], v[16:17] op_sel_hi:[1,0,1] neg_lo:[0,1,0] neg_hi:[0,1,0]
	v_pk_fma_f32 v[8:9], v[146:147], v[30:31], v[18:19] op_sel_hi:[1,0,1] neg_lo:[0,1,0] neg_hi:[0,1,0]
	v_pk_mul_f32 v[24:25], v[10:11], v[148:149] op_sel:[0,0] op_sel_hi:[0,1]
	v_pk_fma_f32 v[24:25], v[10:11], v[150:151], v[24:25] op_sel:[1,0,0] op_sel_hi:[1,1,1]
	v_pk_fma_f32 v[24:25], v[8:9], v[152:153], v[24:25] op_sel:[0,0,0] op_sel_hi:[0,1,1]
	v_pk_fma_f32 v[24:25], v[8:9], v[154:155], v[24:25] op_sel:[1,0,0] op_sel_hi:[1,1,1]
	v_pk_mul_f32 v[20:21], v[80:81], v[160:161] op_sel_hi:[1,0]
	v_pk_mul_f32 v[22:23], v[82:83], v[160:161] op_sel_hi:[1,0]
	v_add_f32_dpp v15, v24, v24 row_ror:8 row_mask:0xf bank_mask:0xf bound_ctrl:1
	v_pk_fma_f32 v[16:17], v[10:11], v[76:77], v[20:21]
	v_pk_fma_f32 v[18:19], v[8:9], v[78:79], v[22:23]
	v_add_f32_dpp v15, v15, v15 row_ror:4 row_mask:0xf bank_mask:0xf bound_ctrl:1
	v_add_f32_dpp v33, v25, v25 row_ror:8 row_mask:0xf bank_mask:0xf bound_ctrl:1
	ds_read_b128 v[116:119], v34 offset:38400
	v_add_f32_dpp v15, v15, v15 row_ror:2 row_mask:0xf bank_mask:0xf bound_ctrl:1
	ds_read_b128 v[120:123], v34 offset:38656
	ds_read_b128 v[124:127], v34 offset:38912
	v_add_f32_dpp v30, v15, v15 row_ror:1 row_mask:0xf bank_mask:0xf bound_ctrl:1
	ds_read_b128 v[128:131], v34 offset:39168
	ds_read_b128 v[132:135], v34 offset:39424
	ds_write2st64_b32 v37, v32, v33 offset0:52 offset1:54
	s_waitcnt lgkmcnt(6)
	v_pk_fma_f32 v[10:11], v[84:85], v[30:31], v[16:17] op_sel_hi:[1,0,1] neg_lo:[0,1,0] neg_hi:[0,1,0]
	v_pk_fma_f32 v[8:9], v[86:87], v[30:31], v[18:19] op_sel_hi:[1,0,1] neg_lo:[0,1,0] neg_hi:[0,1,0]
	v_pk_mul_f32 v[24:25], v[10:11], v[88:89] op_sel:[0,0] op_sel_hi:[0,1]
	v_pk_fma_f32 v[24:25], v[10:11], v[90:91], v[24:25] op_sel:[1,0,0] op_sel_hi:[1,1,1]
	v_pk_fma_f32 v[24:25], v[8:9], v[92:93], v[24:25] op_sel:[0,0,0] op_sel_hi:[0,1,1]
	v_pk_fma_f32 v[24:25], v[8:9], v[94:95], v[24:25] op_sel:[1,0,0] op_sel_hi:[1,1,1]
	v_pk_mul_f32 v[20:21], v[100:101], v[160:161] op_sel:[0,1] op_sel_hi:[1,1]
	v_pk_mul_f32 v[22:23], v[102:103], v[160:161] op_sel:[0,1] op_sel_hi:[1,1]
	v_add_f32_dpp v15, v24, v24 row_ror:8 row_mask:0xf bank_mask:0xf bound_ctrl:1
	v_pk_fma_f32 v[16:17], v[10:11], v[96:97], v[20:21]
	v_pk_fma_f32 v[18:19], v[8:9], v[98:99], v[22:23]
	v_add_f32_dpp v15, v15, v15 row_ror:4 row_mask:0xf bank_mask:0xf bound_ctrl:1
	v_add_f32_dpp v32, v25, v25 row_ror:8 row_mask:0xf bank_mask:0xf bound_ctrl:1
	ds_read_b128 v[136:139], v34 offset:39680
	v_add_f32_dpp v15, v15, v15 row_ror:2 row_mask:0xf bank_mask:0xf bound_ctrl:1
	ds_read_b128 v[140:143], v34 offset:39936
	ds_read_b128 v[144:147], v34 offset:40192
	v_add_f32_dpp v30, v15, v15 row_ror:1 row_mask:0xf bank_mask:0xf bound_ctrl:1
	ds_read_b128 v[148:151], v34 offset:40448
	ds_read_b128 v[152:155], v34 offset:40704
	v_readfirstlane_b32 s54, v56
	s_add_u32 s64, s6, 2
	s_cmp_lt_u32 s54, s64
	s_cbranch_scc1 .Lss_spin_0
.Lss_ok_0:
	s_waitcnt lgkmcnt(5)
	v_pk_fma_f32 v[10:11], v[104:105], v[30:31], v[16:17] op_sel_hi:[1,0,1] neg_lo:[0,1,0] neg_hi:[0,1,0]
	v_pk_fma_f32 v[8:9], v[106:107], v[30:31], v[18:19] op_sel_hi:[1,0,1] neg_lo:[0,1,0] neg_hi:[0,1,0]
	v_pk_mul_f32 v[24:25], v[10:11], v[108:109] op_sel:[0,0] op_sel_hi:[0,1]
	v_pk_fma_f32 v[24:25], v[10:11], v[110:111], v[24:25] op_sel:[1,0,0] op_sel_hi:[1,1,1]
	v_pk_fma_f32 v[24:25], v[8:9], v[112:113], v[24:25] op_sel:[0,0,0] op_sel_hi:[0,1,1]
	v_pk_fma_f32 v[24:25], v[8:9], v[114:115], v[24:25] op_sel:[1,0,0] op_sel_hi:[1,1,1]
	v_pk_mul_f32 v[20:21], v[120:121], v[162:163] op_sel_hi:[1,0]
	v_pk_mul_f32 v[22:23], v[122:123], v[162:163] op_sel_hi:[1,0]
	v_add_f32_dpp v15, v24, v24 row_ror:8 row_mask:0xf bank_mask:0xf bound_ctrl:1
	v_pk_fma_f32 v[16:17], v[10:11], v[116:117], v[20:21]
	v_pk_fma_f32 v[18:19], v[8:9], v[118:119], v[22:23]
	v_add_f32_dpp v15, v15, v15 row_ror:4 row_mask:0xf bank_mask:0xf bound_ctrl:1
	v_add_f32_dpp v33, v25, v25 row_ror:8 row_mask:0xf bank_mask:0xf bound_ctrl:1
	ds_read_b128 v[76:79], v48 offset:0
	v_add_f32_dpp v15, v15, v15 row_ror:2 row_mask:0xf bank_mask:0xf bound_ctrl:1
	ds_read_b128 v[80:83], v48 offset:256
	ds_read_b128 v[84:87], v48 offset:512
	v_add_f32_dpp v30, v15, v15 row_ror:1 row_mask:0xf bank_mask:0xf bound_ctrl:1
	ds_read_b128 v[88:91], v48 offset:768
	ds_read_b128 v[92:95], v48 offset:1024
	ds_write2st64_b32 v37, v32, v33 offset0:56 offset1:58
	ds_read_b128 v[40:43], v48 offset:41728
	ds_read_b128 v[44:47], v48 offset:41984
	ds_read_b128 v[156:159], v49 offset:0
	s_waitcnt lgkmcnt(9)
	v_pk_fma_f32 v[10:11], v[124:125], v[30:31], v[16:17] op_sel_hi:[1,0,1] neg_lo:[0,1,0] neg_hi:[0,1,0]
	v_pk_fma_f32 v[8:9], v[126:127], v[30:31], v[18:19] op_sel_hi:[1,0,1] neg_lo:[0,1,0] neg_hi:[0,1,0]
	v_pk_mul_f32 v[24:25], v[10:11], v[128:129] op_sel:[0,0] op_sel_hi:[0,1]
	v_pk_fma_f32 v[24:25], v[10:11], v[130:131], v[24:25] op_sel:[1,0,0] op_sel_hi:[1,1,1]
	v_pk_fma_f32 v[24:25], v[8:9], v[132:133], v[24:25] op_sel:[0,0,0] op_sel_hi:[0,1,1]
	v_pk_fma_f32 v[24:25], v[8:9], v[134:135], v[24:25] op_sel:[1,0,0] op_sel_hi:[1,1,1]
	v_pk_mul_f32 v[20:21], v[140:141], v[162:163] op_sel:[0,1] op_sel_hi:[1,1]
	v_pk_mul_f32 v[22:23], v[142:143], v[162:163] op_sel:[0,1] op_sel_hi:[1,1]
	v_add_f32_dpp v15, v24, v24 row_ror:8 row_mask:0xf bank_mask:0xf bound_ctrl:1
	v_pk_fma_f32 v[16:17], v[10:11], v[136:137], v[20:21]
	v_pk_fma_f32 v[18:19], v[8:9], v[138:139], v[22:23]
	v_add_f32_dpp v15, v15, v15 row_ror:4 row_mask:0xf bank_mask:0xf bound_ctrl:1
	v_add_f32_dpp v32, v25, v25 row_ror:8 row_mask:0xf bank_mask:0xf bound_ctrl:1
	ds_read_b128 v[96:99], v48 offset:1280
	v_add_f32_dpp v15, v15, v15 row_ror:2 row_mask:0xf bank_mask:0xf bound_ctrl:1
	ds_read_b128 v[100:103], v48 offset:1536
	ds_read_b128 v[104:107], v48 offset:1792
	v_add_f32_dpp v30, v15, v15 row_ror:1 row_mask:0xf bank_mask:0xf bound_ctrl:1
	ds_read_b128 v[108:111], v48 offset:2048
	ds_read_b128 v[112:115], v48 offset:2304
	s_waitcnt lgkmcnt(5)
	v_pk_fma_f32 v[10:11], v[144:145], v[30:31], v[16:17] op_sel_hi:[1,0,1] neg_lo:[0,1,0] neg_hi:[0,1,0]
	v_pk_fma_f32 v[8:9], v[146:147], v[30:31], v[18:19] op_sel_hi:[1,0,1] neg_lo:[0,1,0] neg_hi:[0,1,0]
	v_pk_mul_f32 v[24:25], v[10:11], v[148:149] op_sel:[0,0] op_sel_hi:[0,1]
	v_pk_fma_f32 v[24:25], v[10:11], v[150:151], v[24:25] op_sel:[1,0,0] op_sel_hi:[1,1,1]
	v_pk_fma_f32 v[24:25], v[8:9], v[152:153], v[24:25] op_sel:[0,0,0] op_sel_hi:[0,1,1]
	v_pk_fma_f32 v[24:25], v[8:9], v[154:155], v[24:25] op_sel:[1,0,0] op_sel_hi:[1,1,1]
	s_nop 1
	v_add_f32_dpp v33, v25, v25 row_ror:8 row_mask:0xf bank_mask:0xf bound_ctrl:1
	ds_read_b128 v[116:119], v48 offset:2560
	ds_read_b128 v[120:123], v48 offset:2816
	ds_read_b128 v[124:127], v48 offset:3072
	ds_read_b128 v[128:131], v48 offset:3328
	ds_read_b128 v[132:135], v48 offset:3584
	ds_write2st64_b32 v37, v32, v33 offset0:60 offset1:62
	v_mul_f32_e32 v24, v10, v40
	v_fmac_f32_e32 v24, v11, v42
	v_fmac_f32_e32 v24, v8, v44
	v_fmac_f32_e32 v24, v9, v46
	v_pk_mul_f32 v[20:21], v[80:81], v[156:157] op_sel_hi:[1,0]
	v_pk_mul_f32 v[22:23], v[82:83], v[156:157] op_sel_hi:[1,0]
	v_add_f32_dpp v15, v24, v24 row_ror:8 row_mask:0xf bank_mask:0xf bound_ctrl:1
	v_pk_fma_f32 v[16:17], v[10:11], v[76:77], v[20:21]
	v_pk_fma_f32 v[18:19], v[8:9], v[78:79], v[22:23]
	v_add_f32_dpp v15, v15, v15 row_ror:4 row_mask:0xf bank_mask:0xf bound_ctrl:1
	v_add_u32_e32 v51, 1, v51
	s_add_u32 s6, s6, 1
	v_add_f32_dpp v15, v15, v15 row_ror:2 row_mask:0xf bank_mask:0xf bound_ctrl:1
	ds_write_b32 v53, v51
	s_nop 0
	v_add_f32_dpp v30, v15, v15 row_ror:1 row_mask:0xf bank_mask:0xf bound_ctrl:1
	s_waitcnt lgkmcnt(1)
	v_pk_fma_f32 v[10:11], v[84:85], v[30:31], v[16:17] op_sel_hi:[1,0,1] neg_lo:[0,1,0] neg_hi:[0,1,0]
	v_pk_fma_f32 v[8:9], v[86:87], v[30:31], v[18:19] op_sel_hi:[1,0,1] neg_lo:[0,1,0] neg_hi:[0,1,0]
	v_pk_mul_f32 v[24:25], v[10:11], v[88:89] op_sel:[0,0] op_sel_hi:[0,1]
	v_pk_fma_f32 v[24:25], v[10:11], v[90:91], v[24:25] op_sel:[1,0,0] op_sel_hi:[1,1,1]
	v_pk_fma_f32 v[24:25], v[8:9], v[92:93], v[24:25] op_sel:[0,0,0] op_sel_hi:[0,1,1]
	v_pk_fma_f32 v[24:25], v[8:9], v[94:95], v[24:25] op_sel:[1,0,0] op_sel_hi:[1,1,1]
	v_pk_mul_f32 v[20:21], v[100:101], v[156:157] op_sel:[0,1] op_sel_hi:[1,1]
	v_pk_mul_f32 v[22:23], v[102:103], v[156:157] op_sel:[0,1] op_sel_hi:[1,1]
	v_add_f32_dpp v15, v24, v24 row_ror:8 row_mask:0xf bank_mask:0xf bound_ctrl:1
	v_pk_fma_f32 v[16:17], v[10:11], v[96:97], v[20:21]
	v_pk_fma_f32 v[18:19], v[8:9], v[98:99], v[22:23]
	v_add_f32_dpp v15, v15, v15 row_ror:4 row_mask:0xf bank_mask:0xf bound_ctrl:1
	v_add_f32_dpp v32, v25, v25 row_ror:8 row_mask:0xf bank_mask:0xf bound_ctrl:1
	ds_read_b128 v[136:139], v48 offset:3840
	v_add_f32_dpp v15, v15, v15 row_ror:2 row_mask:0xf bank_mask:0xf bound_ctrl:1
	ds_read_b128 v[140:143], v48 offset:4096
	ds_read_b128 v[144:147], v48 offset:4352
	v_add_f32_dpp v30, v15, v15 row_ror:1 row_mask:0xf bank_mask:0xf bound_ctrl:1
	ds_read_b128 v[148:151], v48 offset:4608
	ds_read_b128 v[152:155], v48 offset:4864
	ds_read_b128 v[160:163], v49 offset:16
	s_waitcnt lgkmcnt(6)
	v_pk_fma_f32 v[10:11], v[104:105], v[30:31], v[16:17] op_sel_hi:[1,0,1] neg_lo:[0,1,0] neg_hi:[0,1,0]
	v_pk_fma_f32 v[8:9], v[106:107], v[30:31], v[18:19] op_sel_hi:[1,0,1] neg_lo:[0,1,0] neg_hi:[0,1,0]
	v_pk_mul_f32 v[24:25], v[10:11], v[108:109] op_sel:[0,0] op_sel_hi:[0,1]
	v_pk_fma_f32 v[24:25], v[10:11], v[110:111], v[24:25] op_sel:[1,0,0] op_sel_hi:[1,1,1]
	v_pk_fma_f32 v[24:25], v[8:9], v[112:113], v[24:25] op_sel:[0,0,0] op_sel_hi:[0,1,1]
	v_pk_fma_f32 v[24:25], v[8:9], v[114:115], v[24:25] op_sel:[1,0,0] op_sel_hi:[1,1,1]
	v_pk_mul_f32 v[20:21], v[120:121], v[158:159] op_sel_hi:[1,0]
	v_pk_mul_f32 v[22:23], v[122:123], v[158:159] op_sel_hi:[1,0]
	v_add_f32_dpp v15, v24, v24 row_ror:8 row_mask:0xf bank_mask:0xf bound_ctrl:1
	v_pk_fma_f32 v[16:17], v[10:11], v[116:117], v[20:21]
	v_pk_fma_f32 v[18:19], v[8:9], v[118:119], v[22:23]
	v_add_f32_dpp v15, v15, v15 row_ror:4 row_mask:0xf bank_mask:0xf bound_ctrl:1
	v_add_f32_dpp v33, v25, v25 row_ror:8 row_mask:0xf bank_mask:0xf bound_ctrl:1
	ds_read_b128 v[76:79], v48 offset:5120
	v_add_f32_dpp v15, v15, v15 row_ror:2 row_mask:0xf bank_mask:0xf bound_ctrl:1
	ds_read_b128 v[80:83], v48 offset:5376
	ds_read_b128 v[84:87], v48 offset:5632
	v_add_f32_dpp v30, v15, v15 row_ror:1 row_mask:0xf bank_mask:0xf bound_ctrl:1
	ds_read_b128 v[88:91], v48 offset:5888
	ds_read_b128 v[92:95], v48 offset:6144
	ds_write2st64_b32 v50, v32, v33 offset0:0 offset1:2
	s_waitcnt lgkmcnt(6)
	v_pk_fma_f32 v[10:11], v[124:125], v[30:31], v[16:17] op_sel_hi:[1,0,1] neg_lo:[0,1,0] neg_hi:[0,1,0]
	v_pk_fma_f32 v[8:9], v[126:127], v[30:31], v[18:19] op_sel_hi:[1,0,1] neg_lo:[0,1,0] neg_hi:[0,1,0]
	v_pk_mul_f32 v[24:25], v[10:11], v[128:129] op_sel:[0,0] op_sel_hi:[0,1]
	v_pk_fma_f32 v[24:25], v[10:11], v[130:131], v[24:25] op_sel:[1,0,0] op_sel_hi:[1,1,1]
	v_pk_fma_f32 v[24:25], v[8:9], v[132:133], v[24:25] op_sel:[0,0,0] op_sel_hi:[0,1,1]
	v_pk_fma_f32 v[24:25], v[8:9], v[134:135], v[24:25] op_sel:[1,0,0] op_sel_hi:[1,1,1]
	v_pk_mul_f32 v[20:21], v[140:141], v[158:159] op_sel:[0,1] op_sel_hi:[1,1]
	v_pk_mul_f32 v[22:23], v[142:143], v[158:159] op_sel:[0,1] op_sel_hi:[1,1]
	v_add_f32_dpp v15, v24, v24 row_ror:8 row_mask:0xf bank_mask:0xf bound_ctrl:1
	v_pk_fma_f32 v[16:17], v[10:11], v[136:137], v[20:21]
	v_pk_fma_f32 v[18:19], v[8:9], v[138:139], v[22:23]
	v_add_f32_dpp v15, v15, v15 row_ror:4 row_mask:0xf bank_mask:0xf bound_ctrl:1
	v_add_f32_dpp v32, v25, v25 row_ror:8 row_mask:0xf bank_mask:0xf bound_ctrl:1
	ds_read_b128 v[96:99], v48 offset:6400
	v_add_f32_dpp v15, v15, v15 row_ror:2 row_mask:0xf bank_mask:0xf bound_ctrl:1
	ds_read_b128 v[100:103], v48 offset:6656
	ds_read_b128 v[104:107], v48 offset:6912
	v_add_f32_dpp v30, v15, v15 row_ror:1 row_mask:0xf bank_mask:0xf bound_ctrl:1
	ds_read_b128 v[108:111], v48 offset:7168
	ds_read_b128 v[112:115], v48 offset:7424
	s_waitcnt lgkmcnt(5)
	v_pk_fma_f32 v[10:11], v[144:145], v[30:31], v[16:17] op_sel_hi:[1,0,1] neg_lo:[0,1,0] neg_hi:[0,1,0]
	v_pk_fma_f32 v[8:9], v[146:147], v[30:31], v[18:19] op_sel_hi:[1,0,1] neg_lo:[0,1,0] neg_hi:[0,1,0]
	v_pk_mul_f32 v[24:25], v[10:11], v[148:149] op_sel:[0,0] op_sel_hi:[0,1]
	v_pk_fma_f32 v[24:25], v[10:11], v[150:151], v[24:25] op_sel:[1,0,0] op_sel_hi:[1,1,1]
	v_pk_fma_f32 v[24:25], v[8:9], v[152:153], v[24:25] op_sel:[0,0,0] op_sel_hi:[0,1,1]
	v_pk_fma_f32 v[24:25], v[8:9], v[154:155], v[24:25] op_sel:[1,0,0] op_sel_hi:[1,1,1]
	v_pk_mul_f32 v[20:21], v[80:81], v[160:161] op_sel_hi:[1,0]
	v_pk_mul_f32 v[22:23], v[82:83], v[160:161] op_sel_hi:[1,0]
	v_add_f32_dpp v15, v24, v24 row_ror:8 row_mask:0xf bank_mask:0xf bound_ctrl:1
	v_pk_fma_f32 v[16:17], v[10:11], v[76:77], v[20:21]
	v_pk_fma_f32 v[18:19], v[8:9], v[78:79], v[22:23]
	v_add_f32_dpp v15, v15, v15 row_ror:4 row_mask:0xf bank_mask:0xf bound_ctrl:1
	v_add_f32_dpp v33, v25, v25 row_ror:8 row_mask:0xf bank_mask:0xf bound_ctrl:1
	ds_read_b128 v[116:119], v48 offset:7680
	v_add_f32_dpp v15, v15, v15 row_ror:2 row_mask:0xf bank_mask:0xf bound_ctrl:1
	ds_read_b128 v[120:123], v48 offset:7936
	ds_read_b128 v[124:127], v48 offset:8192
	v_add_f32_dpp v30, v15, v15 row_ror:1 row_mask:0xf bank_mask:0xf bound_ctrl:1
	ds_read_b128 v[128:131], v48 offset:8448
	ds_read_b128 v[132:135], v48 offset:8704
	ds_write2st64_b32 v50, v32, v33 offset0:4 offset1:6
	s_waitcnt lgkmcnt(6)
	v_pk_fma_f32 v[10:11], v[84:85], v[30:31], v[16:17] op_sel_hi:[1,0,1] neg_lo:[0,1,0] neg_hi:[0,1,0]
	v_pk_fma_f32 v[8:9], v[86:87], v[30:31], v[18:19] op_sel_hi:[1,0,1] neg_lo:[0,1,0] neg_hi:[0,1,0]
	v_pk_mul_f32 v[24:25], v[10:11], v[88:89] op_sel:[0,0] op_sel_hi:[0,1]
	v_pk_fma_f32 v[24:25], v[10:11], v[90:91], v[24:25] op_sel:[1,0,0] op_sel_hi:[1,1,1]
	v_pk_fma_f32 v[24:25], v[8:9], v[92:93], v[24:25] op_sel:[0,0,0] op_sel_hi:[0,1,1]
	v_pk_fma_f32 v[24:25], v[8:9], v[94:95], v[24:25] op_sel:[1,0,0] op_sel_hi:[1,1,1]
	v_pk_mul_f32 v[20:21], v[100:101], v[160:161] op_sel:[0,1] op_sel_hi:[1,1]
	v_pk_mul_f32 v[22:23], v[102:103], v[160:161] op_sel:[0,1] op_sel_hi:[1,1]
	v_add_f32_dpp v15, v24, v24 row_ror:8 row_mask:0xf bank_mask:0xf bound_ctrl:1
	v_pk_fma_f32 v[16:17], v[10:11], v[96:97], v[20:21]
	v_pk_fma_f32 v[18:19], v[8:9], v[98:99], v[22:23]
	v_add_f32_dpp v15, v15, v15 row_ror:4 row_mask:0xf bank_mask:0xf bound_ctrl:1
	v_add_f32_dpp v32, v25, v25 row_ror:8 row_mask:0xf bank_mask:0xf bound_ctrl:1
	ds_read_b128 v[136:139], v48 offset:8960
	v_add_f32_dpp v15, v15, v15 row_ror:2 row_mask:0xf bank_mask:0xf bound_ctrl:1
	ds_read_b128 v[140:143], v48 offset:9216
	ds_read_b128 v[144:147], v48 offset:9472
	v_add_f32_dpp v30, v15, v15 row_ror:1 row_mask:0xf bank_mask:0xf bound_ctrl:1
	ds_read_b128 v[148:151], v48 offset:9728
	ds_read_b128 v[152:155], v48 offset:9984
	ds_read_b128 v[156:159], v49 offset:32
	s_waitcnt lgkmcnt(6)
	v_pk_fma_f32 v[10:11], v[104:105], v[30:31], v[16:17] op_sel_hi:[1,0,1] neg_lo:[0,1,0] neg_hi:[0,1,0]
	v_pk_fma_f32 v[8:9], v[106:107], v[30:31], v[18:19] op_sel_hi:[1,0,1] neg_lo:[0,1,0] neg_hi:[0,1,0]
	v_pk_mul_f32 v[24:25], v[10:11], v[108:109] op_sel:[0,0] op_sel_hi:[0,1]
	v_pk_fma_f32 v[24:25], v[10:11], v[110:111], v[24:25] op_sel:[1,0,0] op_sel_hi:[1,1,1]
	v_pk_fma_f32 v[24:25], v[8:9], v[112:113], v[24:25] op_sel:[0,0,0] op_sel_hi:[0,1,1]
	v_pk_fma_f32 v[24:25], v[8:9], v[114:115], v[24:25] op_sel:[1,0,0] op_sel_hi:[1,1,1]
	v_pk_mul_f32 v[20:21], v[120:121], v[162:163] op_sel_hi:[1,0]
	v_pk_mul_f32 v[22:23], v[122:123], v[162:163] op_sel_hi:[1,0]
	v_add_f32_dpp v15, v24, v24 row_ror:8 row_mask:0xf bank_mask:0xf bound_ctrl:1
	v_pk_fma_f32 v[16:17], v[10:11], v[116:117], v[20:21]
	v_pk_fma_f32 v[18:19], v[8:9], v[118:119], v[22:23]
	v_add_f32_dpp v15, v15, v15 row_ror:4 row_mask:0xf bank_mask:0xf bound_ctrl:1
	v_add_f32_dpp v33, v25, v25 row_ror:8 row_mask:0xf bank_mask:0xf bound_ctrl:1
	ds_read_b128 v[76:79], v48 offset:10240
	v_add_f32_dpp v15, v15, v15 row_ror:2 row_mask:0xf bank_mask:0xf bound_ctrl:1
	ds_read_b128 v[80:83], v48 offset:10496
	ds_read_b128 v[84:87], v48 offset:10752
	v_add_f32_dpp v30, v15, v15 row_ror:1 row_mask:0xf bank_mask:0xf bound_ctrl:1
	ds_read_b128 v[88:91], v48 offset:11008
	ds_read_b128 v[92:95], v48 offset:11264
	ds_write2st64_b32 v50, v32, v33 offset0:8 offset1:10
	s_waitcnt lgkmcnt(6)
	v_pk_fma_f32 v[10:11], v[124:125], v[30:31], v[16:17] op_sel_hi:[1,0,1] neg_lo:[0,1,0] neg_hi:[0,1,0]
	v_pk_fma_f32 v[8:9], v[126:127], v[30:31], v[18:19] op_sel_hi:[1,0,1] neg_lo:[0,1,0] neg_hi:[0,1,0]
	v_pk_mul_f32 v[24:25], v[10:11], v[128:129] op_sel:[0,0] op_sel_hi:[0,1]
	v_pk_fma_f32 v[24:25], v[10:11], v[130:131], v[24:25] op_sel:[1,0,0] op_sel_hi:[1,1,1]
	v_pk_fma_f32 v[24:25], v[8:9], v[132:133], v[24:25] op_sel:[0,0,0] op_sel_hi:[0,1,1]
	v_pk_fma_f32 v[24:25], v[8:9], v[134:135], v[24:25] op_sel:[1,0,0] op_sel_hi:[1,1,1]
	v_pk_mul_f32 v[20:21], v[140:141], v[162:163] op_sel:[0,1] op_sel_hi:[1,1]
	v_pk_mul_f32 v[22:23], v[142:143], v[162:163] op_sel:[0,1] op_sel_hi:[1,1]
	v_add_f32_dpp v15, v24, v24 row_ror:8 row_mask:0xf bank_mask:0xf bound_ctrl:1
	v_pk_fma_f32 v[16:17], v[10:11], v[136:137], v[20:21]
	v_pk_fma_f32 v[18:19], v[8:9], v[138:139], v[22:23]
	v_add_f32_dpp v15, v15, v15 row_ror:4 row_mask:0xf bank_mask:0xf bound_ctrl:1
	v_add_f32_dpp v32, v25, v25 row_ror:8 row_mask:0xf bank_mask:0xf bound_ctrl:1
	ds_read_b128 v[96:99], v48 offset:11520
	v_add_f32_dpp v15, v15, v15 row_ror:2 row_mask:0xf bank_mask:0xf bound_ctrl:1
	ds_read_b128 v[100:103], v48 offset:11776
	ds_read_b128 v[104:107], v48 offset:12032
	v_add_f32_dpp v30, v15, v15 row_ror:1 row_mask:0xf bank_mask:0xf bound_ctrl:1
	ds_read_b128 v[108:111], v48 offset:12288
	ds_read_b128 v[112:115], v48 offset:12544
	s_waitcnt lgkmcnt(5)
	v_pk_fma_f32 v[10:11], v[144:145], v[30:31], v[16:17] op_sel_hi:[1,0,1] neg_lo:[0,1,0] neg_hi:[0,1,0]
	v_pk_fma_f32 v[8:9], v[146:147], v[30:31], v[18:19] op_sel_hi:[1,0,1] neg_lo:[0,1,0] neg_hi:[0,1,0]
	v_pk_mul_f32 v[24:25], v[10:11], v[148:149] op_sel:[0,0] op_sel_hi:[0,1]
	v_pk_fma_f32 v[24:25], v[10:11], v[150:151], v[24:25] op_sel:[1,0,0] op_sel_hi:[1,1,1]
	v_pk_fma_f32 v[24:25], v[8:9], v[152:153], v[24:25] op_sel:[0,0,0] op_sel_hi:[0,1,1]
	v_pk_fma_f32 v[24:25], v[8:9], v[154:155], v[24:25] op_sel:[1,0,0] op_sel_hi:[1,1,1]
	v_pk_mul_f32 v[20:21], v[80:81], v[156:157] op_sel_hi:[1,0]
	v_pk_mul_f32 v[22:23], v[82:83], v[156:157] op_sel_hi:[1,0]
	v_add_f32_dpp v15, v24, v24 row_ror:8 row_mask:0xf bank_mask:0xf bound_ctrl:1
	v_pk_fma_f32 v[16:17], v[10:11], v[76:77], v[20:21]
	v_pk_fma_f32 v[18:19], v[8:9], v[78:79], v[22:23]
	v_add_f32_dpp v15, v15, v15 row_ror:4 row_mask:0xf bank_mask:0xf bound_ctrl:1
	v_add_f32_dpp v33, v25, v25 row_ror:8 row_mask:0xf bank_mask:0xf bound_ctrl:1
	ds_read_b128 v[116:119], v48 offset:12800
	v_add_f32_dpp v15, v15, v15 row_ror:2 row_mask:0xf bank_mask:0xf bound_ctrl:1
	ds_read_b128 v[120:123], v48 offset:13056
	ds_read_b128 v[124:127], v48 offset:13312
	v_add_f32_dpp v30, v15, v15 row_ror:1 row_mask:0xf bank_mask:0xf bound_ctrl:1
	ds_read_b128 v[128:131], v48 offset:13568
	ds_read_b128 v[132:135], v48 offset:13824
	ds_write2st64_b32 v50, v32, v33 offset0:12 offset1:14
	s_waitcnt lgkmcnt(6)
	v_pk_fma_f32 v[10:11], v[84:85], v[30:31], v[16:17] op_sel_hi:[1,0,1] neg_lo:[0,1,0] neg_hi:[0,1,0]
	v_pk_fma_f32 v[8:9], v[86:87], v[30:31], v[18:19] op_sel_hi:[1,0,1] neg_lo:[0,1,0] neg_hi:[0,1,0]
	v_pk_mul_f32 v[24:25], v[10:11], v[88:89] op_sel:[0,0] op_sel_hi:[0,1]
	v_pk_fma_f32 v[24:25], v[10:11], v[90:91], v[24:25] op_sel:[1,0,0] op_sel_hi:[1,1,1]
	v_pk_fma_f32 v[24:25], v[8:9], v[92:93], v[24:25] op_sel:[0,0,0] op_sel_hi:[0,1,1]
	v_pk_fma_f32 v[24:25], v[8:9], v[94:95], v[24:25] op_sel:[1,0,0] op_sel_hi:[1,1,1]
	v_pk_mul_f32 v[20:21], v[100:101], v[156:157] op_sel:[0,1] op_sel_hi:[1,1]
	v_pk_mul_f32 v[22:23], v[102:103], v[156:157] op_sel:[0,1] op_sel_hi:[1,1]
	v_add_f32_dpp v15, v24, v24 row_ror:8 row_mask:0xf bank_mask:0xf bound_ctrl:1
	v_pk_fma_f32 v[16:17], v[10:11], v[96:97], v[20:21]
	v_pk_fma_f32 v[18:19], v[8:9], v[98:99], v[22:23]
	v_add_f32_dpp v15, v15, v15 row_ror:4 row_mask:0xf bank_mask:0xf bound_ctrl:1
	v_add_f32_dpp v32, v25, v25 row_ror:8 row_mask:0xf bank_mask:0xf bound_ctrl:1
	ds_read_b128 v[136:139], v48 offset:14080
	v_add_f32_dpp v15, v15, v15 row_ror:2 row_mask:0xf bank_mask:0xf bound_ctrl:1
	ds_read_b128 v[140:143], v48 offset:14336
	ds_read_b128 v[144:147], v48 offset:14592
	v_add_f32_dpp v30, v15, v15 row_ror:1 row_mask:0xf bank_mask:0xf bound_ctrl:1
	ds_read_b128 v[148:151], v48 offset:14848
	ds_read_b128 v[152:155], v48 offset:15104
	ds_read_b128 v[160:163], v49 offset:48
	s_waitcnt lgkmcnt(6)
	v_pk_fma_f32 v[10:11], v[104:105], v[30:31], v[16:17] op_sel_hi:[1,0,1] neg_lo:[0,1,0] neg_hi:[0,1,0]
	v_pk_fma_f32 v[8:9], v[106:107], v[30:31], v[18:19] op_sel_hi:[1,0,1] neg_lo:[0,1,0] neg_hi:[0,1,0]
	v_pk_mul_f32 v[24:25], v[10:11], v[108:109] op_sel:[0,0] op_sel_hi:[0,1]
	v_pk_fma_f32 v[24:25], v[10:11], v[110:111], v[24:25] op_sel:[1,0,0] op_sel_hi:[1,1,1]
	v_pk_fma_f32 v[24:25], v[8:9], v[112:113], v[24:25] op_sel:[0,0,0] op_sel_hi:[0,1,1]
	v_pk_fma_f32 v[24:25], v[8:9], v[114:115], v[24:25] op_sel:[1,0,0] op_sel_hi:[1,1,1]
	v_pk_mul_f32 v[20:21], v[120:121], v[158:159] op_sel_hi:[1,0]
	v_pk_mul_f32 v[22:23], v[122:123], v[158:159] op_sel_hi:[1,0]
	v_add_f32_dpp v15, v24, v24 row_ror:8 row_mask:0xf bank_mask:0xf bound_ctrl:1
	v_pk_fma_f32 v[16:17], v[10:11], v[116:117], v[20:21]
	v_pk_fma_f32 v[18:19], v[8:9], v[118:119], v[22:23]
	v_add_f32_dpp v15, v15, v15 row_ror:4 row_mask:0xf bank_mask:0xf bound_ctrl:1
	v_add_f32_dpp v33, v25, v25 row_ror:8 row_mask:0xf bank_mask:0xf bound_ctrl:1
	ds_read_b128 v[76:79], v48 offset:15360
	v_add_f32_dpp v15, v15, v15 row_ror:2 row_mask:0xf bank_mask:0xf bound_ctrl:1
	ds_read_b128 v[80:83], v48 offset:15616
	ds_read_b128 v[84:87], v48 offset:15872
	v_add_f32_dpp v30, v15, v15 row_ror:1 row_mask:0xf bank_mask:0xf bound_ctrl:1
	ds_read_b128 v[88:91], v48 offset:16128
	ds_read_b128 v[92:95], v48 offset:16384
	ds_write2st64_b32 v50, v32, v33 offset0:16 offset1:18
	s_waitcnt lgkmcnt(6)
	v_pk_fma_f32 v[10:11], v[124:125], v[30:31], v[16:17] op_sel_hi:[1,0,1] neg_lo:[0,1,0] neg_hi:[0,1,0]
	v_pk_fma_f32 v[8:9], v[126:127], v[30:31], v[18:19] op_sel_hi:[1,0,1] neg_lo:[0,1,0] neg_hi:[0,1,0]
	v_pk_mul_f32 v[24:25], v[10:11], v[128:129] op_sel:[0,0] op_sel_hi:[0,1]
	v_pk_fma_f32 v[24:25], v[10:11], v[130:131], v[24:25] op_sel:[1,0,0] op_sel_hi:[1,1,1]
	v_pk_fma_f32 v[24:25], v[8:9], v[132:133], v[24:25] op_sel:[0,0,0] op_sel_hi:[0,1,1]
	v_pk_fma_f32 v[24:25], v[8:9], v[134:135], v[24:25] op_sel:[1,0,0] op_sel_hi:[1,1,1]
	v_pk_mul_f32 v[20:21], v[140:141], v[158:159] op_sel:[0,1] op_sel_hi:[1,1]
	v_pk_mul_f32 v[22:23], v[142:143], v[158:159] op_sel:[0,1] op_sel_hi:[1,1]
	v_add_f32_dpp v15, v24, v24 row_ror:8 row_mask:0xf bank_mask:0xf bound_ctrl:1
	v_pk_fma_f32 v[16:17], v[10:11], v[136:137], v[20:21]
	v_pk_fma_f32 v[18:19], v[8:9], v[138:139], v[22:23]
	v_add_f32_dpp v15, v15, v15 row_ror:4 row_mask:0xf bank_mask:0xf bound_ctrl:1
	v_add_f32_dpp v32, v25, v25 row_ror:8 row_mask:0xf bank_mask:0xf bound_ctrl:1
	ds_read_b128 v[96:99], v48 offset:16640
	v_add_f32_dpp v15, v15, v15 row_ror:2 row_mask:0xf bank_mask:0xf bound_ctrl:1
	ds_read_b128 v[100:103], v48 offset:16896
	ds_read_b128 v[104:107], v48 offset:17152
	v_add_f32_dpp v30, v15, v15 row_ror:1 row_mask:0xf bank_mask:0xf bound_ctrl:1
	ds_read_b128 v[108:111], v48 offset:17408
	ds_read_b128 v[112:115], v48 offset:17664
	s_waitcnt lgkmcnt(5)
	v_pk_fma_f32 v[10:11], v[144:145], v[30:31], v[16:17] op_sel_hi:[1,0,1] neg_lo:[0,1,0] neg_hi:[0,1,0]
	v_pk_fma_f32 v[8:9], v[146:147], v[30:31], v[18:19] op_sel_hi:[1,0,1] neg_lo:[0,1,0] neg_hi:[0,1,0]
	v_pk_mul_f32 v[24:25], v[10:11], v[148:149] op_sel:[0,0] op_sel_hi:[0,1]
	v_pk_fma_f32 v[24:25], v[10:11], v[150:151], v[24:25] op_sel:[1,0,0] op_sel_hi:[1,1,1]
	v_pk_fma_f32 v[24:25], v[8:9], v[152:153], v[24:25] op_sel:[0,0,0] op_sel_hi:[0,1,1]
	v_pk_fma_f32 v[24:25], v[8:9], v[154:155], v[24:25] op_sel:[1,0,0] op_sel_hi:[1,1,1]
	v_pk_mul_f32 v[20:21], v[80:81], v[160:161] op_sel_hi:[1,0]
	v_pk_mul_f32 v[22:23], v[82:83], v[160:161] op_sel_hi:[1,0]
	v_add_f32_dpp v15, v24, v24 row_ror:8 row_mask:0xf bank_mask:0xf bound_ctrl:1
	v_pk_fma_f32 v[16:17], v[10:11], v[76:77], v[20:21]
	v_pk_fma_f32 v[18:19], v[8:9], v[78:79], v[22:23]
	v_add_f32_dpp v15, v15, v15 row_ror:4 row_mask:0xf bank_mask:0xf bound_ctrl:1
	v_add_f32_dpp v33, v25, v25 row_ror:8 row_mask:0xf bank_mask:0xf bound_ctrl:1
	ds_read_b128 v[116:119], v48 offset:17920
	v_add_f32_dpp v15, v15, v15 row_ror:2 row_mask:0xf bank_mask:0xf bound_ctrl:1
	ds_read_b128 v[120:123], v48 offset:18176
	ds_read_b128 v[124:127], v48 offset:18432
	v_add_f32_dpp v30, v15, v15 row_ror:1 row_mask:0xf bank_mask:0xf bound_ctrl:1
	ds_read_b128 v[128:131], v48 offset:18688
	ds_read_b128 v[132:135], v48 offset:18944
	ds_write2st64_b32 v50, v32, v33 offset0:20 offset1:22
	s_waitcnt lgkmcnt(6)
	v_pk_fma_f32 v[10:11], v[84:85], v[30:31], v[16:17] op_sel_hi:[1,0,1] neg_lo:[0,1,0] neg_hi:[0,1,0]
	v_pk_fma_f32 v[8:9], v[86:87], v[30:31], v[18:19] op_sel_hi:[1,0,1] neg_lo:[0,1,0] neg_hi:[0,1,0]
	v_pk_mul_f32 v[24:25], v[10:11], v[88:89] op_sel:[0,0] op_sel_hi:[0,1]
	v_pk_fma_f32 v[24:25], v[10:11], v[90:91], v[24:25] op_sel:[1,0,0] op_sel_hi:[1,1,1]
	v_pk_fma_f32 v[24:25], v[8:9], v[92:93], v[24:25] op_sel:[0,0,0] op_sel_hi:[0,1,1]
	v_pk_fma_f32 v[24:25], v[8:9], v[94:95], v[24:25] op_sel:[1,0,0] op_sel_hi:[1,1,1]
	v_pk_mul_f32 v[20:21], v[100:101], v[160:161] op_sel:[0,1] op_sel_hi:[1,1]
	v_pk_mul_f32 v[22:23], v[102:103], v[160:161] op_sel:[0,1] op_sel_hi:[1,1]
	v_add_f32_dpp v15, v24, v24 row_ror:8 row_mask:0xf bank_mask:0xf bound_ctrl:1
	v_pk_fma_f32 v[16:17], v[10:11], v[96:97], v[20:21]
	v_pk_fma_f32 v[18:19], v[8:9], v[98:99], v[22:23]
	v_add_f32_dpp v15, v15, v15 row_ror:4 row_mask:0xf bank_mask:0xf bound_ctrl:1
	v_add_f32_dpp v32, v25, v25 row_ror:8 row_mask:0xf bank_mask:0xf bound_ctrl:1
	ds_read_b128 v[136:139], v48 offset:19200
	v_add_f32_dpp v15, v15, v15 row_ror:2 row_mask:0xf bank_mask:0xf bound_ctrl:1
	ds_read_b128 v[140:143], v48 offset:19456
	ds_read_b128 v[144:147], v48 offset:19712
	v_add_f32_dpp v30, v15, v15 row_ror:1 row_mask:0xf bank_mask:0xf bound_ctrl:1
	ds_read_b128 v[148:151], v48 offset:19968
	ds_read_b128 v[152:155], v48 offset:20224
	ds_read_b128 v[156:159], v49 offset:64
	s_waitcnt lgkmcnt(6)
	v_pk_fma_f32 v[10:11], v[104:105], v[30:31], v[16:17] op_sel_hi:[1,0,1] neg_lo:[0,1,0] neg_hi:[0,1,0]
	v_pk_fma_f32 v[8:9], v[106:107], v[30:31], v[18:19] op_sel_hi:[1,0,1] neg_lo:[0,1,0] neg_hi:[0,1,0]
	v_pk_mul_f32 v[24:25], v[10:11], v[108:109] op_sel:[0,0] op_sel_hi:[0,1]
	v_pk_fma_f32 v[24:25], v[10:11], v[110:111], v[24:25] op_sel:[1,0,0] op_sel_hi:[1,1,1]
	v_pk_fma_f32 v[24:25], v[8:9], v[112:113], v[24:25] op_sel:[0,0,0] op_sel_hi:[0,1,1]
	v_pk_fma_f32 v[24:25], v[8:9], v[114:115], v[24:25] op_sel:[1,0,0] op_sel_hi:[1,1,1]
	v_pk_mul_f32 v[20:21], v[120:121], v[162:163] op_sel_hi:[1,0]
	v_pk_mul_f32 v[22:23], v[122:123], v[162:163] op_sel_hi:[1,0]
	v_add_f32_dpp v15, v24, v24 row_ror:8 row_mask:0xf bank_mask:0xf bound_ctrl:1
	v_pk_fma_f32 v[16:17], v[10:11], v[116:117], v[20:21]
	v_pk_fma_f32 v[18:19], v[8:9], v[118:119], v[22:23]
	v_add_f32_dpp v15, v15, v15 row_ror:4 row_mask:0xf bank_mask:0xf bound_ctrl:1
	v_add_f32_dpp v33, v25, v25 row_ror:8 row_mask:0xf bank_mask:0xf bound_ctrl:1
	ds_read_b128 v[76:79], v48 offset:20480
	v_add_f32_dpp v15, v15, v15 row_ror:2 row_mask:0xf bank_mask:0xf bound_ctrl:1
	ds_read_b128 v[80:83], v48 offset:20736
	ds_read_b128 v[84:87], v48 offset:20992
	v_add_f32_dpp v30, v15, v15 row_ror:1 row_mask:0xf bank_mask:0xf bound_ctrl:1
	ds_read_b128 v[88:91], v48 offset:21248
	ds_read_b128 v[92:95], v48 offset:21504
	ds_write2st64_b32 v50, v32, v33 offset0:24 offset1:26
	s_waitcnt lgkmcnt(6)
	v_pk_fma_f32 v[10:11], v[124:125], v[30:31], v[16:17] op_sel_hi:[1,0,1] neg_lo:[0,1,0] neg_hi:[0,1,0]
	v_pk_fma_f32 v[8:9], v[126:127], v[30:31], v[18:19] op_sel_hi:[1,0,1] neg_lo:[0,1,0] neg_hi:[0,1,0]
	v_pk_mul_f32 v[24:25], v[10:11], v[128:129] op_sel:[0,0] op_sel_hi:[0,1]
	v_pk_fma_f32 v[24:25], v[10:11], v[130:131], v[24:25] op_sel:[1,0,0] op_sel_hi:[1,1,1]
	v_pk_fma_f32 v[24:25], v[8:9], v[132:133], v[24:25] op_sel:[0,0,0] op_sel_hi:[0,1,1]
	v_pk_fma_f32 v[24:25], v[8:9], v[134:135], v[24:25] op_sel:[1,0,0] op_sel_hi:[1,1,1]
	v_pk_mul_f32 v[20:21], v[140:141], v[162:163] op_sel:[0,1] op_sel_hi:[1,1]
	v_pk_mul_f32 v[22:23], v[142:143], v[162:163] op_sel:[0,1] op_sel_hi:[1,1]
	v_add_f32_dpp v15, v24, v24 row_ror:8 row_mask:0xf bank_mask:0xf bound_ctrl:1
	v_pk_fma_f32 v[16:17], v[10:11], v[136:137], v[20:21]
	v_pk_fma_f32 v[18:19], v[8:9], v[138:139], v[22:23]
	v_add_f32_dpp v15, v15, v15 row_ror:4 row_mask:0xf bank_mask:0xf bound_ctrl:1
	v_add_f32_dpp v32, v25, v25 row_ror:8 row_mask:0xf bank_mask:0xf bound_ctrl:1
	ds_read_b128 v[96:99], v48 offset:21760
	v_add_f32_dpp v15, v15, v15 row_ror:2 row_mask:0xf bank_mask:0xf bound_ctrl:1
	ds_read_b128 v[100:103], v48 offset:22016
	ds_read_b128 v[104:107], v48 offset:22272
	v_add_f32_dpp v30, v15, v15 row_ror:1 row_mask:0xf bank_mask:0xf bound_ctrl:1
	ds_read_b128 v[108:111], v48 offset:22528
	ds_read_b128 v[112:115], v48 offset:22784
	s_waitcnt lgkmcnt(5)
	v_pk_fma_f32 v[10:11], v[144:145], v[30:31], v[16:17] op_sel_hi:[1,0,1] neg_lo:[0,1,0] neg_hi:[0,1,0]
	v_pk_fma_f32 v[8:9], v[146:147], v[30:31], v[18:19] op_sel_hi:[1,0,1] neg_lo:[0,1,0] neg_hi:[0,1,0]
	v_pk_mul_f32 v[24:25], v[10:11], v[148:149] op_sel:[0,0] op_sel_hi:[0,1]
	v_pk_fma_f32 v[24:25], v[10:11], v[150:151], v[24:25] op_sel:[1,0,0] op_sel_hi:[1,1,1]
	v_pk_fma_f32 v[24:25], v[8:9], v[152:153], v[24:25] op_sel:[0,0,0] op_sel_hi:[0,1,1]
	v_pk_fma_f32 v[24:25], v[8:9], v[154:155], v[24:25] op_sel:[1,0,0] op_sel_hi:[1,1,1]
	v_pk_mul_f32 v[20:21], v[80:81], v[156:157] op_sel_hi:[1,0]
	v_pk_mul_f32 v[22:23], v[82:83], v[156:157] op_sel_hi:[1,0]
	v_add_f32_dpp v15, v24, v24 row_ror:8 row_mask:0xf bank_mask:0xf bound_ctrl:1
	v_pk_fma_f32 v[16:17], v[10:11], v[76:77], v[20:21]
	v_pk_fma_f32 v[18:19], v[8:9], v[78:79], v[22:23]
	v_add_f32_dpp v15, v15, v15 row_ror:4 row_mask:0xf bank_mask:0xf bound_ctrl:1
	v_add_f32_dpp v33, v25, v25 row_ror:8 row_mask:0xf bank_mask:0xf bound_ctrl:1
	ds_read_b128 v[116:119], v48 offset:23040
	v_add_f32_dpp v15, v15, v15 row_ror:2 row_mask:0xf bank_mask:0xf bound_ctrl:1
	ds_read_b128 v[120:123], v48 offset:23296
	ds_read_b128 v[124:127], v48 offset:23552
	v_add_f32_dpp v30, v15, v15 row_ror:1 row_mask:0xf bank_mask:0xf bound_ctrl:1
	ds_read_b128 v[128:131], v48 offset:23808
	ds_read_b128 v[132:135], v48 offset:24064
	ds_write2st64_b32 v50, v32, v33 offset0:28 offset1:30
	s_waitcnt lgkmcnt(6)
	v_pk_fma_f32 v[10:11], v[84:85], v[30:31], v[16:17] op_sel_hi:[1,0,1] neg_lo:[0,1,0] neg_hi:[0,1,0]
	v_pk_fma_f32 v[8:9], v[86:87], v[30:31], v[18:19] op_sel_hi:[1,0,1] neg_lo:[0,1,0] neg_hi:[0,1,0]
	v_pk_mul_f32 v[24:25], v[10:11], v[88:89] op_sel:[0,0] op_sel_hi:[0,1]
	v_pk_fma_f32 v[24:25], v[10:11], v[90:91], v[24:25] op_sel:[1,0,0] op_sel_hi:[1,1,1]
	v_pk_fma_f32 v[24:25], v[8:9], v[92:93], v[24:25] op_sel:[0,0,0] op_sel_hi:[0,1,1]
	v_pk_fma_f32 v[24:25], v[8:9], v[94:95], v[24:25] op_sel:[1,0,0] op_sel_hi:[1,1,1]
	v_pk_mul_f32 v[20:21], v[100:101], v[156:157] op_sel:[0,1] op_sel_hi:[1,1]
	v_pk_mul_f32 v[22:23], v[102:103], v[156:157] op_sel:[0,1] op_sel_hi:[1,1]
	v_add_f32_dpp v15, v24, v24 row_ror:8 row_mask:0xf bank_mask:0xf bound_ctrl:1
	v_pk_fma_f32 v[16:17], v[10:11], v[96:97], v[20:21]
	v_pk_fma_f32 v[18:19], v[8:9], v[98:99], v[22:23]
	v_add_f32_dpp v15, v15, v15 row_ror:4 row_mask:0xf bank_mask:0xf bound_ctrl:1
	v_add_f32_dpp v32, v25, v25 row_ror:8 row_mask:0xf bank_mask:0xf bound_ctrl:1
	ds_read_b128 v[136:139], v48 offset:24320
	v_add_f32_dpp v15, v15, v15 row_ror:2 row_mask:0xf bank_mask:0xf bound_ctrl:1
	ds_read_b128 v[140:143], v48 offset:24576
	ds_read_b128 v[144:147], v48 offset:24832
	v_add_f32_dpp v30, v15, v15 row_ror:1 row_mask:0xf bank_mask:0xf bound_ctrl:1
	ds_read_b128 v[148:151], v48 offset:25088
	ds_read_b128 v[152:155], v48 offset:25344
	ds_read_b128 v[160:163], v49 offset:80
	s_waitcnt lgkmcnt(6)
	v_pk_fma_f32 v[10:11], v[104:105], v[30:31], v[16:17] op_sel_hi:[1,0,1] neg_lo:[0,1,0] neg_hi:[0,1,0]
	v_pk_fma_f32 v[8:9], v[106:107], v[30:31], v[18:19] op_sel_hi:[1,0,1] neg_lo:[0,1,0] neg_hi:[0,1,0]
	v_pk_mul_f32 v[24:25], v[10:11], v[108:109] op_sel:[0,0] op_sel_hi:[0,1]
	v_pk_fma_f32 v[24:25], v[10:11], v[110:111], v[24:25] op_sel:[1,0,0] op_sel_hi:[1,1,1]
	v_pk_fma_f32 v[24:25], v[8:9], v[112:113], v[24:25] op_sel:[0,0,0] op_sel_hi:[0,1,1]
	v_pk_fma_f32 v[24:25], v[8:9], v[114:115], v[24:25] op_sel:[1,0,0] op_sel_hi:[1,1,1]
	v_pk_mul_f32 v[20:21], v[120:121], v[158:159] op_sel_hi:[1,0]
	v_pk_mul_f32 v[22:23], v[122:123], v[158:159] op_sel_hi:[1,0]
	v_add_f32_dpp v15, v24, v24 row_ror:8 row_mask:0xf bank_mask:0xf bound_ctrl:1
	v_pk_fma_f32 v[16:17], v[10:11], v[116:117], v[20:21]
	v_pk_fma_f32 v[18:19], v[8:9], v[118:119], v[22:23]
	v_add_f32_dpp v15, v15, v15 row_ror:4 row_mask:0xf bank_mask:0xf bound_ctrl:1
	v_add_f32_dpp v33, v25, v25 row_ror:8 row_mask:0xf bank_mask:0xf bound_ctrl:1
	ds_read_b128 v[76:79], v48 offset:25600
	v_add_f32_dpp v15, v15, v15 row_ror:2 row_mask:0xf bank_mask:0xf bound_ctrl:1
	ds_read_b128 v[80:83], v48 offset:25856
	ds_read_b128 v[84:87], v48 offset:26112
	v_add_f32_dpp v30, v15, v15 row_ror:1 row_mask:0xf bank_mask:0xf bound_ctrl:1
	ds_read_b128 v[88:91], v48 offset:26368
	ds_read_b128 v[92:95], v48 offset:26624
	ds_write2st64_b32 v50, v32, v33 offset0:32 offset1:34
	s_waitcnt lgkmcnt(6)
	v_pk_fma_f32 v[10:11], v[124:125], v[30:31], v[16:17] op_sel_hi:[1,0,1] neg_lo:[0,1,0] neg_hi:[0,1,0]
	v_pk_fma_f32 v[8:9], v[126:127], v[30:31], v[18:19] op_sel_hi:[1,0,1] neg_lo:[0,1,0] neg_hi:[0,1,0]
	v_pk_mul_f32 v[24:25], v[10:11], v[128:129] op_sel:[0,0] op_sel_hi:[0,1]
	v_pk_fma_f32 v[24:25], v[10:11], v[130:131], v[24:25] op_sel:[1,0,0] op_sel_hi:[1,1,1]
	v_pk_fma_f32 v[24:25], v[8:9], v[132:133], v[24:25] op_sel:[0,0,0] op_sel_hi:[0,1,1]
	v_pk_fma_f32 v[24:25], v[8:9], v[134:135], v[24:25] op_sel:[1,0,0] op_sel_hi:[1,1,1]
	v_pk_mul_f32 v[20:21], v[140:141], v[158:159] op_sel:[0,1] op_sel_hi:[1,1]
	v_pk_mul_f32 v[22:23], v[142:143], v[158:159] op_sel:[0,1] op_sel_hi:[1,1]
	v_add_f32_dpp v15, v24, v24 row_ror:8 row_mask:0xf bank_mask:0xf bound_ctrl:1
	v_pk_fma_f32 v[16:17], v[10:11], v[136:137], v[20:21]
	v_pk_fma_f32 v[18:19], v[8:9], v[138:139], v[22:23]
	v_add_f32_dpp v15, v15, v15 row_ror:4 row_mask:0xf bank_mask:0xf bound_ctrl:1
	v_add_f32_dpp v32, v25, v25 row_ror:8 row_mask:0xf bank_mask:0xf bound_ctrl:1
	ds_read_b128 v[96:99], v48 offset:26880
	v_add_f32_dpp v15, v15, v15 row_ror:2 row_mask:0xf bank_mask:0xf bound_ctrl:1
	ds_read_b128 v[100:103], v48 offset:27136
	ds_read_b128 v[104:107], v48 offset:27392
	v_add_f32_dpp v30, v15, v15 row_ror:1 row_mask:0xf bank_mask:0xf bound_ctrl:1
	ds_read_b128 v[108:111], v48 offset:27648
	ds_read_b128 v[112:115], v48 offset:27904
	s_waitcnt lgkmcnt(5)
	v_pk_fma_f32 v[10:11], v[144:145], v[30:31], v[16:17] op_sel_hi:[1,0,1] neg_lo:[0,1,0] neg_hi:[0,1,0]
	v_pk_fma_f32 v[8:9], v[146:147], v[30:31], v[18:19] op_sel_hi:[1,0,1] neg_lo:[0,1,0] neg_hi:[0,1,0]
	v_pk_mul_f32 v[24:25], v[10:11], v[148:149] op_sel:[0,0] op_sel_hi:[0,1]
	v_pk_fma_f32 v[24:25], v[10:11], v[150:151], v[24:25] op_sel:[1,0,0] op_sel_hi:[1,1,1]
	v_pk_fma_f32 v[24:25], v[8:9], v[152:153], v[24:25] op_sel:[0,0,0] op_sel_hi:[0,1,1]
	v_pk_fma_f32 v[24:25], v[8:9], v[154:155], v[24:25] op_sel:[1,0,0] op_sel_hi:[1,1,1]
	v_pk_mul_f32 v[20:21], v[80:81], v[160:161] op_sel_hi:[1,0]
	v_pk_mul_f32 v[22:23], v[82:83], v[160:161] op_sel_hi:[1,0]
	v_add_f32_dpp v15, v24, v24 row_ror:8 row_mask:0xf bank_mask:0xf bound_ctrl:1
	v_pk_fma_f32 v[16:17], v[10:11], v[76:77], v[20:21]
	v_pk_fma_f32 v[18:19], v[8:9], v[78:79], v[22:23]
	v_add_f32_dpp v15, v15, v15 row_ror:4 row_mask:0xf bank_mask:0xf bound_ctrl:1
	v_add_f32_dpp v33, v25, v25 row_ror:8 row_mask:0xf bank_mask:0xf bound_ctrl:1
	ds_read_b128 v[116:119], v48 offset:28160
	v_add_f32_dpp v15, v15, v15 row_ror:2 row_mask:0xf bank_mask:0xf bound_ctrl:1
	ds_read_b128 v[120:123], v48 offset:28416
	ds_read_b128 v[124:127], v48 offset:28672
	v_add_f32_dpp v30, v15, v15 row_ror:1 row_mask:0xf bank_mask:0xf bound_ctrl:1
	ds_read_b128 v[128:131], v48 offset:28928
	ds_read_b128 v[132:135], v48 offset:29184
	ds_write2st64_b32 v50, v32, v33 offset0:36 offset1:38
	s_waitcnt lgkmcnt(6)
	v_pk_fma_f32 v[10:11], v[84:85], v[30:31], v[16:17] op_sel_hi:[1,0,1] neg_lo:[0,1,0] neg_hi:[0,1,0]
	v_pk_fma_f32 v[8:9], v[86:87], v[30:31], v[18:19] op_sel_hi:[1,0,1] neg_lo:[0,1,0] neg_hi:[0,1,0]
	v_pk_mul_f32 v[24:25], v[10:11], v[88:89] op_sel:[0,0] op_sel_hi:[0,1]
	v_pk_fma_f32 v[24:25], v[10:11], v[90:91], v[24:25] op_sel:[1,0,0] op_sel_hi:[1,1,1]
	v_pk_fma_f32 v[24:25], v[8:9], v[92:93], v[24:25] op_sel:[0,0,0] op_sel_hi:[0,1,1]
	v_pk_fma_f32 v[24:25], v[8:9], v[94:95], v[24:25] op_sel:[1,0,0] op_sel_hi:[1,1,1]
	v_pk_mul_f32 v[20:21], v[100:101], v[160:161] op_sel:[0,1] op_sel_hi:[1,1]
	v_pk_mul_f32 v[22:23], v[102:103], v[160:161] op_sel:[0,1] op_sel_hi:[1,1]
	v_add_f32_dpp v15, v24, v24 row_ror:8 row_mask:0xf bank_mask:0xf bound_ctrl:1
	v_pk_fma_f32 v[16:17], v[10:11], v[96:97], v[20:21]
	v_pk_fma_f32 v[18:19], v[8:9], v[98:99], v[22:23]
	v_add_f32_dpp v15, v15, v15 row_ror:4 row_mask:0xf bank_mask:0xf bound_ctrl:1
	v_add_f32_dpp v32, v25, v25 row_ror:8 row_mask:0xf bank_mask:0xf bound_ctrl:1
	ds_read_b128 v[136:139], v48 offset:29440
	v_add_f32_dpp v15, v15, v15 row_ror:2 row_mask:0xf bank_mask:0xf bound_ctrl:1
	ds_read_b128 v[140:143], v48 offset:29696
	ds_read_b128 v[144:147], v48 offset:29952
	v_add_f32_dpp v30, v15, v15 row_ror:1 row_mask:0xf bank_mask:0xf bound_ctrl:1
	ds_read_b128 v[148:151], v48 offset:30208
	ds_read_b128 v[152:155], v48 offset:30464
	ds_read_b128 v[156:159], v49 offset:96
	s_waitcnt lgkmcnt(6)
	v_pk_fma_f32 v[10:11], v[104:105], v[30:31], v[16:17] op_sel_hi:[1,0,1] neg_lo:[0,1,0] neg_hi:[0,1,0]
	v_pk_fma_f32 v[8:9], v[106:107], v[30:31], v[18:19] op_sel_hi:[1,0,1] neg_lo:[0,1,0] neg_hi:[0,1,0]
	v_pk_mul_f32 v[24:25], v[10:11], v[108:109] op_sel:[0,0] op_sel_hi:[0,1]
	v_pk_fma_f32 v[24:25], v[10:11], v[110:111], v[24:25] op_sel:[1,0,0] op_sel_hi:[1,1,1]
	v_pk_fma_f32 v[24:25], v[8:9], v[112:113], v[24:25] op_sel:[0,0,0] op_sel_hi:[0,1,1]
	v_pk_fma_f32 v[24:25], v[8:9], v[114:115], v[24:25] op_sel:[1,0,0] op_sel_hi:[1,1,1]
	v_pk_mul_f32 v[20:21], v[120:121], v[162:163] op_sel_hi:[1,0]
	v_pk_mul_f32 v[22:23], v[122:123], v[162:163] op_sel_hi:[1,0]
	v_add_f32_dpp v15, v24, v24 row_ror:8 row_mask:0xf bank_mask:0xf bound_ctrl:1
	v_pk_fma_f32 v[16:17], v[10:11], v[116:117], v[20:21]
	v_pk_fma_f32 v[18:19], v[8:9], v[118:119], v[22:23]
	v_add_f32_dpp v15, v15, v15 row_ror:4 row_mask:0xf bank_mask:0xf bound_ctrl:1
	v_add_f32_dpp v33, v25, v25 row_ror:8 row_mask:0xf bank_mask:0xf bound_ctrl:1
	ds_read_b128 v[76:79], v48 offset:30720
	v_add_f32_dpp v15, v15, v15 row_ror:2 row_mask:0xf bank_mask:0xf bound_ctrl:1
	ds_read_b128 v[80:83], v48 offset:30976
	ds_read_b128 v[84:87], v48 offset:31232
	v_add_f32_dpp v30, v15, v15 row_ror:1 row_mask:0xf bank_mask:0xf bound_ctrl:1
	ds_read_b128 v[88:91], v48 offset:31488
	ds_read_b128 v[92:95], v48 offset:31744
	ds_write2st64_b32 v50, v32, v33 offset0:40 offset1:42
	s_waitcnt lgkmcnt(6)
	v_pk_fma_f32 v[10:11], v[124:125], v[30:31], v[16:17] op_sel_hi:[1,0,1] neg_lo:[0,1,0] neg_hi:[0,1,0]
	v_pk_fma_f32 v[8:9], v[126:127], v[30:31], v[18:19] op_sel_hi:[1,0,1] neg_lo:[0,1,0] neg_hi:[0,1,0]
	v_pk_mul_f32 v[24:25], v[10:11], v[128:129] op_sel:[0,0] op_sel_hi:[0,1]
	v_pk_fma_f32 v[24:25], v[10:11], v[130:131], v[24:25] op_sel:[1,0,0] op_sel_hi:[1,1,1]
	v_pk_fma_f32 v[24:25], v[8:9], v[132:133], v[24:25] op_sel:[0,0,0] op_sel_hi:[0,1,1]
	v_pk_fma_f32 v[24:25], v[8:9], v[134:135], v[24:25] op_sel:[1,0,0] op_sel_hi:[1,1,1]
	v_pk_mul_f32 v[20:21], v[140:141], v[162:163] op_sel:[0,1] op_sel_hi:[1,1]
	v_pk_mul_f32 v[22:23], v[142:143], v[162:163] op_sel:[0,1] op_sel_hi:[1,1]
	v_add_f32_dpp v15, v24, v24 row_ror:8 row_mask:0xf bank_mask:0xf bound_ctrl:1
	v_pk_fma_f32 v[16:17], v[10:11], v[136:137], v[20:21]
	v_pk_fma_f32 v[18:19], v[8:9], v[138:139], v[22:23]
	v_add_f32_dpp v15, v15, v15 row_ror:4 row_mask:0xf bank_mask:0xf bound_ctrl:1
	v_add_f32_dpp v32, v25, v25 row_ror:8 row_mask:0xf bank_mask:0xf bound_ctrl:1
	ds_read_b128 v[96:99], v48 offset:32000
	v_add_f32_dpp v15, v15, v15 row_ror:2 row_mask:0xf bank_mask:0xf bound_ctrl:1
	ds_read_b128 v[100:103], v48 offset:32256
	ds_read_b128 v[104:107], v48 offset:32512
	v_add_f32_dpp v30, v15, v15 row_ror:1 row_mask:0xf bank_mask:0xf bound_ctrl:1
	ds_read_b128 v[108:111], v48 offset:32768
	ds_read_b128 v[112:115], v48 offset:33024
	s_waitcnt lgkmcnt(5)
	v_pk_fma_f32 v[10:11], v[144:145], v[30:31], v[16:17] op_sel_hi:[1,0,1] neg_lo:[0,1,0] neg_hi:[0,1,0]
	v_pk_fma_f32 v[8:9], v[146:147], v[30:31], v[18:19] op_sel_hi:[1,0,1] neg_lo:[0,1,0] neg_hi:[0,1,0]
	v_pk_mul_f32 v[24:25], v[10:11], v[148:149] op_sel:[0,0] op_sel_hi:[0,1]
	v_pk_fma_f32 v[24:25], v[10:11], v[150:151], v[24:25] op_sel:[1,0,0] op_sel_hi:[1,1,1]
	v_pk_fma_f32 v[24:25], v[8:9], v[152:153], v[24:25] op_sel:[0,0,0] op_sel_hi:[0,1,1]
	v_pk_fma_f32 v[24:25], v[8:9], v[154:155], v[24:25] op_sel:[1,0,0] op_sel_hi:[1,1,1]
	v_pk_mul_f32 v[20:21], v[80:81], v[156:157] op_sel_hi:[1,0]
	v_pk_mul_f32 v[22:23], v[82:83], v[156:157] op_sel_hi:[1,0]
	v_add_f32_dpp v15, v24, v24 row_ror:8 row_mask:0xf bank_mask:0xf bound_ctrl:1
	v_pk_fma_f32 v[16:17], v[10:11], v[76:77], v[20:21]
	v_pk_fma_f32 v[18:19], v[8:9], v[78:79], v[22:23]
	v_add_f32_dpp v15, v15, v15 row_ror:4 row_mask:0xf bank_mask:0xf bound_ctrl:1
	v_add_f32_dpp v33, v25, v25 row_ror:8 row_mask:0xf bank_mask:0xf bound_ctrl:1
	ds_read_b128 v[116:119], v48 offset:33280
	v_add_f32_dpp v15, v15, v15 row_ror:2 row_mask:0xf bank_mask:0xf bound_ctrl:1
	ds_read_b128 v[120:123], v48 offset:33536
	ds_read_b128 v[124:127], v48 offset:33792
	v_add_f32_dpp v30, v15, v15 row_ror:1 row_mask:0xf bank_mask:0xf bound_ctrl:1
	ds_read_b128 v[128:131], v48 offset:34048
	ds_read_b128 v[132:135], v48 offset:34304
	ds_write2st64_b32 v50, v32, v33 offset0:44 offset1:46
	s_waitcnt lgkmcnt(6)
	v_pk_fma_f32 v[10:11], v[84:85], v[30:31], v[16:17] op_sel_hi:[1,0,1] neg_lo:[0,1,0] neg_hi:[0,1,0]
	v_pk_fma_f32 v[8:9], v[86:87], v[30:31], v[18:19] op_sel_hi:[1,0,1] neg_lo:[0,1,0] neg_hi:[0,1,0]
	v_pk_mul_f32 v[24:25], v[10:11], v[88:89] op_sel:[0,0] op_sel_hi:[0,1]
	v_pk_fma_f32 v[24:25], v[10:11], v[90:91], v[24:25] op_sel:[1,0,0] op_sel_hi:[1,1,1]
	v_pk_fma_f32 v[24:25], v[8:9], v[92:93], v[24:25] op_sel:[0,0,0] op_sel_hi:[0,1,1]
	v_pk_fma_f32 v[24:25], v[8:9], v[94:95], v[24:25] op_sel:[1,0,0] op_sel_hi:[1,1,1]
	v_pk_mul_f32 v[20:21], v[100:101], v[156:157] op_sel:[0,1] op_sel_hi:[1,1]
	v_pk_mul_f32 v[22:23], v[102:103], v[156:157] op_sel:[0,1] op_sel_hi:[1,1]
	v_add_f32_dpp v15, v24, v24 row_ror:8 row_mask:0xf bank_mask:0xf bound_ctrl:1
	v_pk_fma_f32 v[16:17], v[10:11], v[96:97], v[20:21]
	v_pk_fma_f32 v[18:19], v[8:9], v[98:99], v[22:23]
	v_add_f32_dpp v15, v15, v15 row_ror:4 row_mask:0xf bank_mask:0xf bound_ctrl:1
	v_add_f32_dpp v32, v25, v25 row_ror:8 row_mask:0xf bank_mask:0xf bound_ctrl:1
	ds_read_b128 v[136:139], v48 offset:34560
	v_add_f32_dpp v15, v15, v15 row_ror:2 row_mask:0xf bank_mask:0xf bound_ctrl:1
	ds_read_b128 v[140:143], v48 offset:34816
	ds_read_b128 v[144:147], v48 offset:35072
	v_add_f32_dpp v30, v15, v15 row_ror:1 row_mask:0xf bank_mask:0xf bound_ctrl:1
	ds_read_b128 v[148:151], v48 offset:35328
	ds_read_b128 v[152:155], v48 offset:35584
	ds_read_b128 v[160:163], v49 offset:112
	s_waitcnt lgkmcnt(6)
	v_pk_fma_f32 v[10:11], v[104:105], v[30:31], v[16:17] op_sel_hi:[1,0,1] neg_lo:[0,1,0] neg_hi:[0,1,0]
	v_pk_fma_f32 v[8:9], v[106:107], v[30:31], v[18:19] op_sel_hi:[1,0,1] neg_lo:[0,1,0] neg_hi:[0,1,0]
	v_pk_mul_f32 v[24:25], v[10:11], v[108:109] op_sel:[0,0] op_sel_hi:[0,1]
	v_pk_fma_f32 v[24:25], v[10:11], v[110:111], v[24:25] op_sel:[1,0,0] op_sel_hi:[1,1,1]
	v_pk_fma_f32 v[24:25], v[8:9], v[112:113], v[24:25] op_sel:[0,0,0] op_sel_hi:[0,1,1]
	v_pk_fma_f32 v[24:25], v[8:9], v[114:115], v[24:25] op_sel:[1,0,0] op_sel_hi:[1,1,1]
	v_pk_mul_f32 v[20:21], v[120:121], v[158:159] op_sel_hi:[1,0]
	v_pk_mul_f32 v[22:23], v[122:123], v[158:159] op_sel_hi:[1,0]
	v_add_f32_dpp v15, v24, v24 row_ror:8 row_mask:0xf bank_mask:0xf bound_ctrl:1
	v_pk_fma_f32 v[16:17], v[10:11], v[116:117], v[20:21]
	v_pk_fma_f32 v[18:19], v[8:9], v[118:119], v[22:23]
	v_add_f32_dpp v15, v15, v15 row_ror:4 row_mask:0xf bank_mask:0xf bound_ctrl:1
	v_add_f32_dpp v33, v25, v25 row_ror:8 row_mask:0xf bank_mask:0xf bound_ctrl:1
	ds_read_b128 v[76:79], v48 offset:35840
	v_add_f32_dpp v15, v15, v15 row_ror:2 row_mask:0xf bank_mask:0xf bound_ctrl:1
	ds_read_b128 v[80:83], v48 offset:36096
	ds_read_b128 v[84:87], v48 offset:36352
	v_add_f32_dpp v30, v15, v15 row_ror:1 row_mask:0xf bank_mask:0xf bound_ctrl:1
	ds_read_b128 v[88:91], v48 offset:36608
	ds_read_b128 v[92:95], v48 offset:36864
	ds_write2st64_b32 v50, v32, v33 offset0:48 offset1:50
	ds_read_b128 v[56:59], v52
	s_waitcnt lgkmcnt(6)
	v_pk_fma_f32 v[10:11], v[124:125], v[30:31], v[16:17] op_sel_hi:[1,0,1] neg_lo:[0,1,0] neg_hi:[0,1,0]
	v_pk_fma_f32 v[8:9], v[126:127], v[30:31], v[18:19] op_sel_hi:[1,0,1] neg_lo:[0,1,0] neg_hi:[0,1,0]
	v_pk_mul_f32 v[24:25], v[10:11], v[128:129] op_sel:[0,0] op_sel_hi:[0,1]
	v_pk_fma_f32 v[24:25], v[10:11], v[130:131], v[24:25] op_sel:[1,0,0] op_sel_hi:[1,1,1]
	v_pk_fma_f32 v[24:25], v[8:9], v[132:133], v[24:25] op_sel:[0,0,0] op_sel_hi:[0,1,1]
	v_pk_fma_f32 v[24:25], v[8:9], v[134:135], v[24:25] op_sel:[1,0,0] op_sel_hi:[1,1,1]
	v_pk_mul_f32 v[20:21], v[140:141], v[158:159] op_sel:[0,1] op_sel_hi:[1,1]
	v_pk_mul_f32 v[22:23], v[142:143], v[158:159] op_sel:[0,1] op_sel_hi:[1,1]
	v_add_f32_dpp v15, v24, v24 row_ror:8 row_mask:0xf bank_mask:0xf bound_ctrl:1
	v_pk_fma_f32 v[16:17], v[10:11], v[136:137], v[20:21]
	v_pk_fma_f32 v[18:19], v[8:9], v[138:139], v[22:23]
	v_add_f32_dpp v15, v15, v15 row_ror:4 row_mask:0xf bank_mask:0xf bound_ctrl:1
	v_add_f32_dpp v32, v25, v25 row_ror:8 row_mask:0xf bank_mask:0xf bound_ctrl:1
	ds_read_b128 v[96:99], v48 offset:37120
	v_add_f32_dpp v15, v15, v15 row_ror:2 row_mask:0xf bank_mask:0xf bound_ctrl:1
	ds_read_b128 v[100:103], v48 offset:37376
	ds_read_b128 v[104:107], v48 offset:37632
	v_add_f32_dpp v30, v15, v15 row_ror:1 row_mask:0xf bank_mask:0xf bound_ctrl:1
	ds_read_b128 v[108:111], v48 offset:37888
	ds_read_b128 v[112:115], v48 offset:38144
	s_waitcnt lgkmcnt(5)
	v_min_u32_e32 v56, v56, v57
	v_min3_u32 v56, v56, v58, v59
	v_pk_fma_f32 v[10:11], v[144:145], v[30:31], v[16:17] op_sel_hi:[1,0,1] neg_lo:[0,1,0] neg_hi:[0,1,0]
	v_pk_fma_f32 v[8:9], v[146:147], v[30:31], v[18:19] op_sel_hi:[1,0,1] neg_lo:[0,1,0] neg_hi:[0,1,0]
	v_pk_mul_f32 v[24:25], v[10:11], v[148:149] op_sel:[0,0] op_sel_hi:[0,1]
	v_pk_fma_f32 v[24:25], v[10:11], v[150:151], v[24:25] op_sel:[1,0,0] op_sel_hi:[1,1,1]
	v_pk_fma_f32 v[24:25], v[8:9], v[152:153], v[24:25] op_sel:[0,0,0] op_sel_hi:[0,1,1]
	v_pk_fma_f32 v[24:25], v[8:9], v[154:155], v[24:25] op_sel:[1,0,0] op_sel_hi:[1,1,1]
	v_pk_mul_f32 v[20:21], v[80:81], v[160:161] op_sel_hi:[1,0]
	v_pk_mul_f32 v[22:23], v[82:83], v[160:161] op_sel_hi:[1,0]
	v_add_f32_dpp v15, v24, v24 row_ror:8 row_mask:0xf bank_mask:0xf bound_ctrl:1
	v_pk_fma_f32 v[16:17], v[10:11], v[76:77], v[20:21]
	v_pk_fma_f32 v[18:19], v[8:9], v[78:79], v[22:23]
	v_add_f32_dpp v15, v15, v15 row_ror:4 row_mask:0xf bank_mask:0xf bound_ctrl:1
	v_add_f32_dpp v33, v25, v25 row_ror:8 row_mask:0xf bank_mask:0xf bound_ctrl:1
	ds_read_b128 v[116:119], v48 offset:38400
	v_add_f32_dpp v15, v15, v15 row_ror:2 row_mask:0xf bank_mask:0xf bound_ctrl:1
	ds_read_b128 v[120:123], v48 offset:38656
	ds_read_b128 v[124:127], v48 offset:38912
	v_add_f32_dpp v30, v15, v15 row_ror:1 row_mask:0xf bank_mask:0xf bound_ctrl:1
	ds_read_b128 v[128:131], v48 offset:39168
	ds_read_b128 v[132:135], v48 offset:39424
	ds_write2st64_b32 v50, v32, v33 offset0:52 offset1:54
	s_waitcnt lgkmcnt(6)
	v_pk_fma_f32 v[10:11], v[84:85], v[30:31], v[16:17] op_sel_hi:[1,0,1] neg_lo:[0,1,0] neg_hi:[0,1,0]
	v_pk_fma_f32 v[8:9], v[86:87], v[30:31], v[18:19] op_sel_hi:[1,0,1] neg_lo:[0,1,0] neg_hi:[0,1,0]
	v_pk_mul_f32 v[24:25], v[10:11], v[88:89] op_sel:[0,0] op_sel_hi:[0,1]
	v_pk_fma_f32 v[24:25], v[10:11], v[90:91], v[24:25] op_sel:[1,0,0] op_sel_hi:[1,1,1]
	v_pk_fma_f32 v[24:25], v[8:9], v[92:93], v[24:25] op_sel:[0,0,0] op_sel_hi:[0,1,1]
	v_pk_fma_f32 v[24:25], v[8:9], v[94:95], v[24:25] op_sel:[1,0,0] op_sel_hi:[1,1,1]
	v_pk_mul_f32 v[20:21], v[100:101], v[160:161] op_sel:[0,1] op_sel_hi:[1,1]
	v_pk_mul_f32 v[22:23], v[102:103], v[160:161] op_sel:[0,1] op_sel_hi:[1,1]
	v_add_f32_dpp v15, v24, v24 row_ror:8 row_mask:0xf bank_mask:0xf bound_ctrl:1
	v_pk_fma_f32 v[16:17], v[10:11], v[96:97], v[20:21]
	v_pk_fma_f32 v[18:19], v[8:9], v[98:99], v[22:23]
	v_add_f32_dpp v15, v15, v15 row_ror:4 row_mask:0xf bank_mask:0xf bound_ctrl:1
	v_add_f32_dpp v32, v25, v25 row_ror:8 row_mask:0xf bank_mask:0xf bound_ctrl:1
	ds_read_b128 v[136:139], v48 offset:39680
	v_add_f32_dpp v15, v15, v15 row_ror:2 row_mask:0xf bank_mask:0xf bound_ctrl:1
	ds_read_b128 v[140:143], v48 offset:39936
	ds_read_b128 v[144:147], v48 offset:40192
	v_add_f32_dpp v30, v15, v15 row_ror:1 row_mask:0xf bank_mask:0xf bound_ctrl:1
	ds_read_b128 v[148:151], v48 offset:40448
	ds_read_b128 v[152:155], v48 offset:40704
	v_readfirstlane_b32 s54, v56
	s_add_u32 s64, s6, 2
	s_cmp_lt_u32 s54, s64
	s_cbranch_scc1 .Lss_spin_1
.Lss_ok_1:
	s_waitcnt lgkmcnt(5)
	v_pk_fma_f32 v[10:11], v[104:105], v[30:31], v[16:17] op_sel_hi:[1,0,1] neg_lo:[0,1,0] neg_hi:[0,1,0]
	v_pk_fma_f32 v[8:9], v[106:107], v[30:31], v[18:19] op_sel_hi:[1,0,1] neg_lo:[0,1,0] neg_hi:[0,1,0]
	v_pk_mul_f32 v[24:25], v[10:11], v[108:109] op_sel:[0,0] op_sel_hi:[0,1]
	v_pk_fma_f32 v[24:25], v[10:11], v[110:111], v[24:25] op_sel:[1,0,0] op_sel_hi:[1,1,1]
	v_pk_fma_f32 v[24:25], v[8:9], v[112:113], v[24:25] op_sel:[0,0,0] op_sel_hi:[0,1,1]
	v_pk_fma_f32 v[24:25], v[8:9], v[114:115], v[24:25] op_sel:[1,0,0] op_sel_hi:[1,1,1]
	v_pk_mul_f32 v[20:21], v[120:121], v[162:163] op_sel_hi:[1,0]
	v_pk_mul_f32 v[22:23], v[122:123], v[162:163] op_sel_hi:[1,0]
	v_add_f32_dpp v15, v24, v24 row_ror:8 row_mask:0xf bank_mask:0xf bound_ctrl:1
	v_pk_fma_f32 v[16:17], v[10:11], v[116:117], v[20:21]
	v_pk_fma_f32 v[18:19], v[8:9], v[118:119], v[22:23]
	v_add_f32_dpp v15, v15, v15 row_ror:4 row_mask:0xf bank_mask:0xf bound_ctrl:1
	v_add_f32_dpp v33, v25, v25 row_ror:8 row_mask:0xf bank_mask:0xf bound_ctrl:1
	ds_read_b128 v[76:79], v34 offset:0
	v_add_f32_dpp v15, v15, v15 row_ror:2 row_mask:0xf bank_mask:0xf bound_ctrl:1
	ds_read_b128 v[80:83], v34 offset:256
	ds_read_b128 v[84:87], v34 offset:512
	v_add_f32_dpp v30, v15, v15 row_ror:1 row_mask:0xf bank_mask:0xf bound_ctrl:1
	ds_read_b128 v[88:91], v34 offset:768
	ds_read_b128 v[92:95], v34 offset:1024
	ds_write2st64_b32 v50, v32, v33 offset0:56 offset1:58
	ds_read_b128 v[40:43], v34 offset:41728
	ds_read_b128 v[44:47], v34 offset:41984
	ds_read_b128 v[156:159], v35 offset:0
	s_waitcnt lgkmcnt(9)
	v_pk_fma_f32 v[10:11], v[124:125], v[30:31], v[16:17] op_sel_hi:[1,0,1] neg_lo:[0,1,0] neg_hi:[0,1,0]
	v_pk_fma_f32 v[8:9], v[126:127], v[30:31], v[18:19] op_sel_hi:[1,0,1] neg_lo:[0,1,0] neg_hi:[0,1,0]
	v_pk_mul_f32 v[24:25], v[10:11], v[128:129] op_sel:[0,0] op_sel_hi:[0,1]
	v_pk_fma_f32 v[24:25], v[10:11], v[130:131], v[24:25] op_sel:[1,0,0] op_sel_hi:[1,1,1]
	v_pk_fma_f32 v[24:25], v[8:9], v[132:133], v[24:25] op_sel:[0,0,0] op_sel_hi:[0,1,1]
	v_pk_fma_f32 v[24:25], v[8:9], v[134:135], v[24:25] op_sel:[1,0,0] op_sel_hi:[1,1,1]
	v_pk_mul_f32 v[20:21], v[140:141], v[162:163] op_sel:[0,1] op_sel_hi:[1,1]
	v_pk_mul_f32 v[22:23], v[142:143], v[162:163] op_sel:[0,1] op_sel_hi:[1,1]
	v_add_f32_dpp v15, v24, v24 row_ror:8 row_mask:0xf bank_mask:0xf bound_ctrl:1
	v_pk_fma_f32 v[16:17], v[10:11], v[136:137], v[20:21]
	v_pk_fma_f32 v[18:19], v[8:9], v[138:139], v[22:23]
	v_add_f32_dpp v15, v15, v15 row_ror:4 row_mask:0xf bank_mask:0xf bound_ctrl:1
	v_add_f32_dpp v32, v25, v25 row_ror:8 row_mask:0xf bank_mask:0xf bound_ctrl:1
	ds_read_b128 v[96:99], v34 offset:1280
	v_add_f32_dpp v15, v15, v15 row_ror:2 row_mask:0xf bank_mask:0xf bound_ctrl:1
	ds_read_b128 v[100:103], v34 offset:1536
	ds_read_b128 v[104:107], v34 offset:1792
	v_add_f32_dpp v30, v15, v15 row_ror:1 row_mask:0xf bank_mask:0xf bound_ctrl:1
	ds_read_b128 v[108:111], v34 offset:2048
	ds_read_b128 v[112:115], v34 offset:2304
	s_waitcnt lgkmcnt(5)
	v_pk_fma_f32 v[10:11], v[144:145], v[30:31], v[16:17] op_sel_hi:[1,0,1] neg_lo:[0,1,0] neg_hi:[0,1,0]
	v_pk_fma_f32 v[8:9], v[146:147], v[30:31], v[18:19] op_sel_hi:[1,0,1] neg_lo:[0,1,0] neg_hi:[0,1,0]
	v_pk_mul_f32 v[24:25], v[10:11], v[148:149] op_sel:[0,0] op_sel_hi:[0,1]
	v_pk_fma_f32 v[24:25], v[10:11], v[150:151], v[24:25] op_sel:[1,0,0] op_sel_hi:[1,1,1]
	v_pk_fma_f32 v[24:25], v[8:9], v[152:153], v[24:25] op_sel:[0,0,0] op_sel_hi:[0,1,1]
	v_pk_fma_f32 v[24:25], v[8:9], v[154:155], v[24:25] op_sel:[1,0,0] op_sel_hi:[1,1,1]
	s_nop 1
	v_add_f32_dpp v33, v25, v25 row_ror:8 row_mask:0xf bank_mask:0xf bound_ctrl:1
	ds_read_b128 v[116:119], v34 offset:2560
	ds_read_b128 v[120:123], v34 offset:2816
	ds_read_b128 v[124:127], v34 offset:3072
	ds_read_b128 v[128:131], v34 offset:3328
	ds_read_b128 v[132:135], v34 offset:3584
	ds_write2st64_b32 v50, v32, v33 offset0:60 offset1:62
	v_mul_f32_e32 v24, v10, v40
	v_fmac_f32_e32 v24, v11, v42
	v_fmac_f32_e32 v24, v8, v44
	v_fmac_f32_e32 v24, v9, v46
	v_pk_mul_f32 v[20:21], v[80:81], v[156:157] op_sel_hi:[1,0]
	v_pk_mul_f32 v[22:23], v[82:83], v[156:157] op_sel_hi:[1,0]
	v_add_f32_dpp v15, v24, v24 row_ror:8 row_mask:0xf bank_mask:0xf bound_ctrl:1
	v_pk_fma_f32 v[16:17], v[10:11], v[76:77], v[20:21]
	v_pk_fma_f32 v[18:19], v[8:9], v[78:79], v[22:23]
	v_add_f32_dpp v15, v15, v15 row_ror:4 row_mask:0xf bank_mask:0xf bound_ctrl:1
	v_add_u32_e32 v51, 1, v51
	s_add_u32 s6, s6, 1
	v_add_f32_dpp v15, v15, v15 row_ror:2 row_mask:0xf bank_mask:0xf bound_ctrl:1
	ds_write_b32 v53, v51
	s_nop 0
	v_add_f32_dpp v30, v15, v15 row_ror:1 row_mask:0xf bank_mask:0xf bound_ctrl:1
	s_cmp_lt_u32 s6, 0x100
	s_cbranch_scc1 .Lsc_S_loop
	s_waitcnt lgkmcnt(0)
	s_branch .Lsc_item_end
.Lss_spin_0:
	s_mov_b32 s55, 0x100000
.Lss_spin_0_l:
	s_sleep 1
	ds_read_b128 v[56:59], v52
	s_waitcnt lgkmcnt(0)
	v_min_u32_e32 v56, v56, v57
	v_min3_u32 v56, v56, v58, v59
	s_sub_u32 s55, s55, 1
	s_nop 1
	v_readfirstlane_b32 s54, v56
	s_cmp_eq_u32 s55, 0
	s_cbranch_scc1 .Lss_ok_0
	s_cmp_lt_u32 s54, s64
	s_cbranch_scc1 .Lss_spin_0_l
	s_branch .Lss_ok_0

.Lsc_G:
	v_add_u32_e32 v1, 0xffffff00, v173
	v_lshrrev_b32_e32 v2, 3, v1
	v_and_b32_e32 v3, 7, v1
	s_and_b32 s8, s4, 7
	s_bfe_u32 s10, s4, 0x20003
	s_lshr_b32 s11, s4, 7
	s_bfe_u32 s9, s4, 0x20005
	s_lshl_b32 s9, s9, 13
	v_readlane_b32 s50, v242, 0
	v_readlane_b32 s51, v242, 1
	v_readlane_b32 s16, v242, 62
	s_load_dwordx4 s[12:15], s[50:51], 0x68
	s_add_u32 s36, s90, 0x5e00000
	s_addc_u32 s37, s91, 0
	s_add_u32 s38, s90, 0x7e00000
	s_addc_u32 s39, s91, 0
	s_add_u32 s44, s90, 0x9e00000
	s_addc_u32 s45, s91, 0
	s_add_u32 s46, s90, 0x1c00000
	s_addc_u32 s47, s91, 0
	s_lshl_b32 s68, s11, 25
	s_add_u32 s69, s68, 0x13e00000
	s_add_u32 s40, s90, s69
	s_addc_u32 s41, s91, 0
	s_add_u32 s69, s68, 0x17e00000
	s_add_u32 s42, s90, s69
	s_addc_u32 s43, s91, 0
	s_lshl_b32 s68, s11, 26
	s_add_u32 s68, s68, 0xbe00000
	s_add_u32 s48, s90, s68
	s_addc_u32 s49, s91, 0
	s_cmp_eq_u32 s11, 0
	s_mov_b32 s54, 0x8000
	s_movk_i32 s55, 0x400
	s_mov_b32 s64, 0x10000
	s_cselect_b32 s54, s54, 0xffff8000
	s_cselect_b32 s55, s55, 0xfffffc00
	s_cselect_b32 s64, s64, 0xffff0000
	s_cselect_b64 vcc, -1, 0
	v_sub_u32_e32 v4, 0x1fff, v2
	s_nop 3
	v_cndmask_b32_e32 v4, v4, v2, vcc
	v_add_u32_e32 v4, s9, v4
	s_lshl_b32 s68, s8, 7
	v_lshlrev_b32_e32 v5, 10, v4
	v_lshl_add_u32 v5, v3, 3, v5
	v_add_u32_e32 v5, s68, v5
	s_lshl_b32 s69, s8, 2
	v_lshlrev_b32_e32 v6, 5, v4
	v_add_u32_e32 v6, s69, v6
	s_lshl_b32 s69, s10, 5
	s_add_i32 s69, s69, s68
	v_lshlrev_b32_e32 v9, 10, v4
	v_lshl_add_u32 v9, v3, 2, v9
	v_add_u32_e32 v9, s69, v9
	s_lshl_b32 s69, s69, 1
	v_lshlrev_b32_e32 v7, 11, v4
	v_lshl_add_u32 v7, v3, 3, v7
	v_add_u32_e32 v7, s69, v7
	v_mul_u32_u24_e32 v8, 1280, v2
	v_lshl_add_u32 v8, v3, 4, v8
	v_add_u32_e32 v138, 768, v8
	v_add_u32_e32 v140, 43008, v8
	v_add_u32_e32 v139, -1, v2
	v_cmp_eq_u32_e32 vcc, 0, v2
	v_mov_b32_e32 v106, 32
	s_nop 1
	v_cndmask_b32_e32 v139, v139, v106, vcc
	v_mul_u32_u24_e32 v139, 1280, v139
	v_lshl_add_u32 v139, v3, 4, v139
	v_add_u32_e32 v141, 43008, v139
	v_add_u32_e32 v139, 768, v139
	v_mul_u32_u24_e32 v142, 288, v3
	v_lshl_add_u32 v142, v2, 2, v142
	v_add_u32_e32 v143, 86784, v142
	v_add_u32_e32 v142, 84480, v142
	v_lshlrev_b32_e32 v11, 9, v2
	v_lshl_add_u32 v11, v3, 6, v11
	v_add_u32_e32 v11, 89088, v11
	s_lshl_b32 s69, s8, 6
	s_add_i32 s69, s69, s16
	v_lshl_add_u32 v106, v3, 2, s69
	v_lshlrev_b32_e32 v106, 2, v106
	s_waitcnt lgkmcnt(0)
	global_load_dwordx4 v[12:15], v106, s[12:13]
	global_load_dwordx4 v[16:19], v106, s[12:13] offset:128
	global_load_dwordx4 v[20:23], v106, s[14:15]
	global_load_dwordx4 v[24:27], v106, s[14:15] offset:128
	global_load_dwordx2 v[28:29], v5, s[36:37]
	global_load_dwordx2 v[30:31], v5, s[36:37] offset:64
	global_load_dwordx2 v[32:33], v5, s[38:39]
	global_load_dwordx2 v[34:35], v5, s[38:39] offset:64
	global_load_dwordx2 v[36:37], v5, s[40:41]
	global_load_dwordx2 v[38:39], v5, s[40:41] offset:64
	global_load_dwordx2 v[40:41], v5, s[42:43]
	global_load_dwordx2 v[42:43], v5, s[42:43] offset:64
	global_load_dword v44, v6, s[46:47]
	global_load_dword v45, v9, s[44:45]
	v_add_u32_e32 v5, s54, v5
	v_add_u32_e32 v6, s55, v6
	v_add_u32_e32 v9, s54, v9
	global_load_dwordx2 v[46:47], v5, s[36:37]
	global_load_dwordx2 v[48:49], v5, s[36:37] offset:64
	global_load_dwordx2 v[50:51], v5, s[38:39]
	global_load_dwordx2 v[52:53], v5, s[38:39] offset:64
	global_load_dwordx2 v[54:55], v5, s[40:41]
	global_load_dwordx2 v[56:57], v5, s[40:41] offset:64
	global_load_dwordx2 v[58:59], v5, s[42:43]
	global_load_dwordx2 v[60:61], v5, s[42:43] offset:64
	global_load_dword v62, v6, s[46:47]
	global_load_dword v63, v9, s[44:45]
	v_add_u32_e32 v5, s54, v5
	v_add_u32_e32 v6, s55, v6
	v_add_u32_e32 v9, s54, v9
	s_mov_b32 s6, 0
	v_mov_b32_e32 v144, 121872
	v_mov_b32_e32 v145, v164
	v_mov_b32_e32 v146, 0
.Lsc_G_loop:
	s_cmp_lt_u32 s6, 2
	s_cbranch_scc1 .Lsc_G_go0
	s_sub_u32 s65, s6, 1
	s_mov_b32 s69, 0x100000
.Lsc_G_poll0:
	ds_read_b128 v[148:151], v144
	s_waitcnt lgkmcnt(0)
	v_min_u32_e32 v148, v148, v149
	v_min3_u32 v148, v148, v150, v151
	s_sub_u32 s69, s69, 1
	s_nop 1
	v_readfirstlane_b32 s68, v148
	s_cmp_eq_u32 s69, 0
	s_cbranch_scc1 .Lsc_G_go0
	s_cmp_ge_u32 s68, s65
	s_cbranch_scc1 .Lsc_G_go0
	s_sleep 2
	s_branch .Lsc_G_poll0

.Lsc_G_skipstage0:
	s_cmp_ge_u32 s6, 0xfe
	s_cbranch_scc1 .Lsc_G_nostage0
	global_load_dwordx2 v[28:29], v5, s[36:37]
	global_load_dwordx2 v[30:31], v5, s[36:37] offset:64
	global_load_dwordx2 v[32:33], v5, s[38:39]
	global_load_dwordx2 v[34:35], v5, s[38:39] offset:64
	global_load_dwordx2 v[36:37], v5, s[40:41]
	global_load_dwordx2 v[38:39], v5, s[40:41] offset:64
	global_load_dwordx2 v[40:41], v5, s[42:43]
	global_load_dwordx2 v[42:43], v5, s[42:43] offset:64
	global_load_dword v44, v6, s[46:47]
	global_load_dword v45, v9, s[44:45]
	v_add_u32_e32 v5, s54, v5
	v_add_u32_e32 v6, s55, v6
	v_add_u32_e32 v9, s54, v9

.Lsc_G_noy0:
	s_add_i32 s6, s6, 1
	v_add_u32_e32 v146, 1, v146
	s_waitcnt lgkmcnt(0)
	ds_write_b32 v145, v146
	s_cmp_lt_u32 s6, 2
	s_cbranch_scc1 .Lsc_G_go1
	s_sub_u32 s65, s6, 1
	s_mov_b32 s69, 0x100000

.Lsc_G_skipstage1:
	s_cmp_ge_u32 s6, 0xfe
	s_cbranch_scc1 .Lsc_G_nostage1
	global_load_dwordx2 v[46:47], v5, s[36:37]
	global_load_dwordx2 v[48:49], v5, s[36:37] offset:64
	global_load_dwordx2 v[50:51], v5, s[38:39]
	global_load_dwordx2 v[52:53], v5, s[38:39] offset:64
	global_load_dwordx2 v[54:55], v5, s[40:41]
	global_load_dwordx2 v[56:57], v5, s[40:41] offset:64
	global_load_dwordx2 v[58:59], v5, s[42:43]
	global_load_dwordx2 v[60:61], v5, s[42:43] offset:64
	global_load_dword v62, v6, s[46:47]
	global_load_dword v63, v9, s[44:45]
	v_add_u32_e32 v5, s54, v5
	v_add_u32_e32 v6, s55, v6
	v_add_u32_e32 v9, s54, v9

.Lsc_G_noy1:
	s_add_i32 s6, s6, 1
	v_add_u32_e32 v146, 1, v146
	s_waitcnt lgkmcnt(0)
	ds_write_b32 v145, v146
	s_cmp_lg_u32 s6, 0x102
	s_cbranch_scc1 .Lsc_G_loop
